# RMSNorm phases: residual-stream row loads without the non-temporal hint (v130 feature set)
# baseline (speedup 1.0000x reference)
; DI void phase_ln(const Params& p, int layer, int sub, bool first, bool final_, const u16* M, int glayer, int goff) {
;     ...
;   const int nw = gridDim.x * 8, gw = blockIdx.x * 8 + w;
;   const int rows_per = (NTOK + nw - 1) / nw;
;   const int r0 = gw * rows_per;
;   const int r1 = (r0 + rows_per < NTOK) ? (r0 + rows_per) : NTOK;
;   if (r0 >= r1) return;
;   auto load_row = [&](int row, float4 (&v)[4], u32x2 (&mm)[4]) {
;     const float* xr = first ? xin_row(p, row) : (p.out + (size_t)row * DM);
; #pragma unroll
;     for (int j = 0; j < 4; ++j) {
;       const f32x4v t_ = __builtin_nontemporal_load((const f32x4v*)(xr + j * 256 + lane * 4));
;       v[j] = (float4){t_.x, t_.y, t_.z, t_.w};
;     }
;     if (M) {
; #pragma unroll
;       for (int j = 0; j < 4; ++j) mm[j] = *(const u32x2*)(M + (size_t)row * DM + j * 256 + lane * 4);
;     }
;   };
;   float4 pg[4], psh[4], pgm[4];
;   int cur_bb = -1;
;   float4 v[4], vn[4], vn2[4];
;   u32x2 mm[4], mmn[4], mmn2[4];
; #pragma unroll
;   for (int j = 0; j < 4; ++j) {
;     mm[j] = (u32x2){0u, 0u}; mmn[j] = (u32x2){0u, 0u}; mmn2[j] = (u32x2){0u, 0u};
;     vn[j] = (float4){0.f, 0.f, 0.f, 0.f}; vn2[j] = (float4){0.f, 0.f, 0.f, 0.f};
;   }
;   load_row(r0, v, mm);
;   if (r0 + 1 < r1) load_row(r0 + 1, vn, mmn);
;   for (int row = r0; row < r1; ++row) {
;     if (row + 2 < r1) load_row(row + 2, vn2, mmn2);
.LBB0_32:
	s_mov_b64 s[6:7], -1
	s_cmp_lt_i32 s84, 8
	s_mov_b64 s[10:11], 0
	s_movk_i32 s24, 0x1800
	s_mov_b64 s[26:27], 0x800
	v_writelane_b32 v255, s84, 6
	s_cbranch_scc1 .LBB0_158
	s_cmp_gt_i32 s84, 11
	s_cbranch_scc0 .LBB0_92
	s_cmp_gt_i32 s84, 13
	s_cbranch_scc0 .LBB0_46
	s_cmp_gt_i32 s84, 14
	s_mov_b64 s[8:9], -1
	s_cbranch_scc0 .LBB0_49
	s_cmp_eq_u32 s84, 15
	s_cbranch_scc0 .LBB0_48
	v_mov_b32_e32 v40, v204
	s_load_dword s6, s[74:75], 0x0
	s_waitcnt vmcnt(7)
	v_ashrrev_i32_e32 v2, 6, v40
	v_readlane_b32 s8, v253, 14
	s_waitcnt lgkmcnt(0)
	s_lshl_b32 s6, s6, 3
	s_abs_i32 s7, s6
	v_cvt_f32_u32_e32 v0, s7
	s_sub_i32 s9, 0, s7
	v_add_u32_e32 v2, s8, v2
	s_add_i32 s8, s6, 0xbfff
	v_rcp_iflag_f32_e32 v0, v0
	s_xor_b32 s6, s8, s6
	s_abs_i32 s8, s8
	s_ashr_i32 s6, s6, 31
	v_mul_f32_e32 v0, 0x4f7ffffe, v0
	v_cvt_u32_f32_e32 v0, v0
	s_nop 0
	v_readfirstlane_b32 s10, v0
	s_mul_i32 s9, s9, s10
	s_mul_hi_u32 s9, s10, s9
	s_add_i32 s10, s10, s9
	s_mul_hi_u32 s9, s8, s10
	s_mul_i32 s10, s9, s7
	s_sub_i32 s8, s8, s10
	s_add_i32 s11, s9, 1
	s_sub_i32 s10, s8, s7
	s_cmp_ge_u32 s8, s7
	s_cselect_b32 s9, s11, s9
	s_cselect_b32 s8, s10, s8
	s_add_i32 s10, s9, 1
	s_cmp_ge_u32 s8, s7
	s_cselect_b32 s7, s10, s9
	s_xor_b32 s7, s7, s6
	s_sub_i32 s6, s7, s6
	v_mul_lo_u32 v82, s6, v2
	v_add_u32_e32 v0, s6, v82
	v_min_i32_e32 v120, 0xc000, v0
	v_cmp_lt_i32_e32 vcc, v82, v120
	s_and_saveexec_b64 s[6:7], vcc
	s_cbranch_execz .LBB0_47
	v_ashrrev_i32_e32 v83, 31, v82
	v_lshlrev_b32_e32 v0, 2, v40
	v_lshlrev_b64 v[34:35], 12, v[82:83]
	v_and_b32_e32 v4, 0xfc, v0
	v_lshl_add_u64 v[2:3], s[68:69], 0, v[34:35]
	v_lshlrev_b32_e32 v0, 2, v4
	v_lshl_add_u64 v[2:3], v[2:3], 0, v[0:1]
	global_load_dwordx4 v[26:29], v[2:3], off
	global_load_dwordx4 v[30:33], v[2:3], off offset:1024
	global_load_dwordx4 v[18:21], v[2:3], off offset:2048
	global_load_dwordx4 v[22:25], v[2:3], off offset:3072
	v_lshlrev_b64 v[2:3], 11, v[82:83]
	v_lshl_add_u64 v[2:3], s[90:91], 0, v[2:3]
	v_lshlrev_b32_e32 v36, 1, v4
	v_mov_b32_e32 v37, v1
	v_lshl_add_u64 v[2:3], v[2:3], 0, v[36:37]
	global_load_dwordx2 v[102:103], v[2:3], off
	global_load_dwordx2 v[100:101], v[2:3], off offset:512
	global_load_dwordx2 v[96:97], v[2:3], off offset:1024
	global_load_dwordx2 v[94:95], v[2:3], off offset:1536
	v_add_u32_e32 v38, 1, v82
	v_cmp_lt_i32_e32 vcc, v38, v120
	v_mov_b32_e32 v2, 0
	v_mov_b32_e32 v84, 0
	v_mov_b32_e32 v86, 0
	v_mov_b32_e32 v87, 0
	v_mov_b32_e32 v88, 0
	v_mov_b32_e32 v89, 0
	v_mov_b32_e32 v90, 0
	v_mov_b32_e32 v91, 0
	v_mov_b32_e32 v92, 0
	v_mov_b32_e32 v93, 0
	v_mov_b32_e32 v3, 0
	v_mov_b32_e32 v4, 0
	v_mov_b32_e32 v5, 0
	s_waitcnt vmcnt(14)
	v_mov_b32_e32 v6, 0
	v_mov_b32_e32 v7, 0
	v_mov_b32_e32 v8, 0
	v_mov_b32_e32 v9, 0
	s_waitcnt vmcnt(13)
	v_mov_b32_e32 v10, 0
	v_mov_b32_e32 v11, 0
	v_mov_b32_e32 v12, 0
	v_mov_b32_e32 v13, 0
	s_waitcnt vmcnt(12)
	v_mov_b32_e32 v14, 0
	v_mov_b32_e32 v15, 0
	v_mov_b32_e32 v16, 0
	v_mov_b32_e32 v17, 0
	s_and_saveexec_b64 s[8:9], vcc
	s_cbranch_execz .LBB0_40
	v_ashrrev_i32_e32 v39, 31, v38
	v_lshlrev_b64 v[2:3], 12, v[38:39]
	v_lshlrev_b64 v[38:39], 11, v[38:39]
	v_lshl_add_u64 v[2:3], s[68:69], 0, v[2:3]
	v_lshl_add_u64 v[38:39], s[90:91], 0, v[38:39]
	v_lshl_add_u64 v[14:15], v[2:3], 0, v[0:1]
	v_lshl_add_u64 v[38:39], v[38:39], 0, v[36:37]
	global_load_dwordx4 v[2:5], v[14:15], off
	global_load_dwordx4 v[6:9], v[14:15], off offset:1024
	global_load_dwordx4 v[10:13], v[14:15], off offset:2048
	s_nop 0
	global_load_dwordx4 v[14:17], v[14:15], off offset:3072
	s_nop 0
	global_load_dwordx2 v[86:87], v[38:39], off
	global_load_dwordx2 v[88:89], v[38:39], off offset:512
	global_load_dwordx2 v[90:91], v[38:39], off offset:1024
	global_load_dwordx2 v[92:93], v[38:39], off offset:1536

; DI void phase_ln(const Params& p, int layer, int sub, bool first, bool final_, const u16* M, int glayer, int goff) {
;     ...
;   auto load_row = [&](int row, float4 (&v)[4], u32x2 (&mm)[4]) {
;     const float* xr = first ? xin_row(p, row) : (p.out + (size_t)row * DM);
; #pragma unroll
;     for (int j = 0; j < 4; ++j) {
;       const f32x4v t_ = __builtin_nontemporal_load((const f32x4v*)(xr + j * 256 + lane * 4));
;       v[j] = (float4){t_.x, t_.y, t_.z, t_.w};
;     }
;     if (M) {
; #pragma unroll
;       for (int j = 0; j < 4; ++j) mm[j] = *(const u32x2*)(M + (size_t)row * DM + j * 256 + lane * 4);
;     }
;     ...
;     if (row + 2 < r1) load_row(row + 2, vn2, mmn2);
.LBB0_42:
	v_add_u32_e32 v118, 2, v82
	v_cmp_lt_i32_e32 vcc, v118, v120
	s_and_saveexec_b64 s[10:11], vcc
	s_cbranch_execz .LBB0_44
	v_ashrrev_i32_e32 v119, 31, v118
	v_lshlrev_b64 v[54:55], 12, v[118:119]
	v_lshlrev_b64 v[84:85], 11, v[118:119]
	v_lshl_add_u64 v[78:79], v[104:105], 0, v[54:55]
	v_lshl_add_u64 v[116:117], v[106:107], 0, v[84:85]
	global_load_dwordx4 v[54:57], v[78:79], off
	global_load_dwordx4 v[70:73], v[78:79], off offset:1024
	global_load_dwordx4 v[74:77], v[78:79], off offset:2048
	s_nop 0
	global_load_dwordx4 v[78:81], v[78:79], off offset:3072
	s_nop 0
	global_load_dwordx2 v[84:85], v[116:117], off
	global_load_dwordx2 v[112:113], v[116:117], off offset:512
	global_load_dwordx2 v[114:115], v[116:117], off offset:1024
	s_nop 0
	global_load_dwordx2 v[116:117], v[116:117], off offset:1536

; DI void phase_ln(const Params& p, int layer, int sub, bool first, bool final_, const u16* M, int glayer, int goff) {
;     ...
;   const int nw = gridDim.x * 8, gw = blockIdx.x * 8 + w;
;   const int rows_per = (NTOK + nw - 1) / nw;
;   const int r0 = gw * rows_per;
;   const int r1 = (r0 + rows_per < NTOK) ? (r0 + rows_per) : NTOK;
;   if (r0 >= r1) return;
;   auto load_row = [&](int row, float4 (&v)[4], u32x2 (&mm)[4]) {
;     const float* xr = first ? xin_row(p, row) : (p.out + (size_t)row * DM);
; #pragma unroll
;     for (int j = 0; j < 4; ++j) {
;       const f32x4v t_ = __builtin_nontemporal_load((const f32x4v*)(xr + j * 256 + lane * 4));
;       v[j] = (float4){t_.x, t_.y, t_.z, t_.w};
;     }
;     if (M) {
; #pragma unroll
;       for (int j = 0; j < 4; ++j) mm[j] = *(const u32x2*)(M + (size_t)row * DM + j * 256 + lane * 4);
;     }
;   };
;   float4 pg[4], psh[4], pgm[4];
;   int cur_bb = -1;
;   float4 v[4], vn[4], vn2[4];
;   u32x2 mm[4], mmn[4], mmn2[4];
; #pragma unroll
;   for (int j = 0; j < 4; ++j) {
;     mm[j] = (u32x2){0u, 0u}; mmn[j] = (u32x2){0u, 0u}; mmn2[j] = (u32x2){0u, 0u};
;     vn[j] = (float4){0.f, 0.f, 0.f, 0.f}; vn2[j] = (float4){0.f, 0.f, 0.f, 0.f};
;   }
;   load_row(r0, v, mm);
;   if (r0 + 1 < r1) load_row(r0 + 1, vn, mmn);
;   for (int row = r0; row < r1; ++row) {
;     if (row + 2 < r1) load_row(row + 2, vn2, mmn2);
.LBB0_80:
	s_and_b64 vcc, exec, s[6:7]
	s_cbranch_vccz .LBB0_91
	v_mov_b32_e32 v42, v204
	s_load_dword s6, s[74:75], 0x0
	s_mov_b64 s[14:15], s[10:11]
	s_waitcnt vmcnt(7)
	v_ashrrev_i32_e32 v2, 6, v42
	v_readlane_b32 s8, v253, 14
	s_waitcnt lgkmcnt(0)
	s_lshl_b32 s6, s6, 3
	s_abs_i32 s7, s6
	v_cvt_f32_u32_e32 v0, s7
	s_sub_i32 s9, 0, s7
	v_add_u32_e32 v2, s8, v2
	s_add_i32 s8, s6, 0xbfff
	v_rcp_iflag_f32_e32 v0, v0
	s_xor_b32 s6, s8, s6
	s_abs_i32 s8, s8
	s_ashr_i32 s6, s6, 31
	v_mul_f32_e32 v0, 0x4f7ffffe, v0
	v_cvt_u32_f32_e32 v0, v0
	s_nop 0
	v_readfirstlane_b32 s10, v0
	s_mul_i32 s9, s9, s10
	s_mul_hi_u32 s9, s10, s9
	s_add_i32 s10, s10, s9
	s_mul_hi_u32 s9, s8, s10
	s_mul_i32 s10, s9, s7
	s_sub_i32 s8, s8, s10
	s_add_i32 s11, s9, 1
	s_sub_i32 s10, s8, s7
	s_cmp_ge_u32 s8, s7
	s_cselect_b32 s9, s11, s9
	s_cselect_b32 s8, s10, s8
	s_add_i32 s10, s9, 1
	s_cmp_ge_u32 s8, s7
	s_cselect_b32 s7, s10, s9
	s_xor_b32 s7, s7, s6
	s_sub_i32 s6, s7, s6
	v_mul_lo_u32 v82, s6, v2
	v_add_u32_e32 v0, s6, v82
	v_min_i32_e32 v150, 0xc000, v0
	v_cmp_lt_i32_e32 vcc, v82, v150
	s_and_saveexec_b64 s[6:7], vcc
	s_cbranch_execz .LBB0_90
	v_ashrrev_i32_e32 v83, 31, v82
	v_lshlrev_b32_e32 v0, 2, v42
	v_lshlrev_b64 v[34:35], 12, v[82:83]
	v_and_b32_e32 v43, 0xfc, v0
	v_lshl_add_u64 v[2:3], s[68:69], 0, v[34:35]
	v_lshlrev_b32_e32 v0, 2, v43
	v_lshl_add_u64 v[2:3], v[2:3], 0, v[0:1]
	v_lshlrev_b64 v[36:37], 11, v[82:83]
	global_load_dwordx4 v[30:33], v[2:3], off
	global_load_dwordx4 v[26:29], v[2:3], off offset:1024
	global_load_dwordx4 v[22:25], v[2:3], off offset:2048
	global_load_dwordx4 v[18:21], v[2:3], off offset:3072
	v_lshl_add_u64 v[2:3], s[2:3], 0, v[36:37]
	v_lshlrev_b32_e32 v38, 1, v43
	v_mov_b32_e32 v39, v1
	v_lshl_add_u64 v[2:3], v[2:3], 0, v[38:39]
	global_load_dwordx2 v[108:109], v[2:3], off
	global_load_dwordx2 v[106:107], v[2:3], off offset:512
	global_load_dwordx2 v[104:105], v[2:3], off offset:1024
	global_load_dwordx2 v[98:99], v[2:3], off offset:1536
	v_add_u32_e32 v40, 1, v82
	v_cmp_lt_i32_e32 vcc, v40, v150
	v_mov_b32_e32 v2, 0
	v_mov_b32_e32 v84, 0
	v_mov_b32_e32 v86, 0
	v_mov_b32_e32 v87, 0
	v_mov_b32_e32 v88, 0
	v_mov_b32_e32 v89, 0
	v_mov_b32_e32 v90, 0
	v_mov_b32_e32 v91, 0
	v_mov_b32_e32 v92, 0
	v_mov_b32_e32 v93, 0
	v_mov_b32_e32 v3, 0
	v_mov_b32_e32 v4, 0
	v_mov_b32_e32 v5, 0
	s_waitcnt vmcnt(14)
	v_mov_b32_e32 v6, 0
	v_mov_b32_e32 v7, 0
	v_mov_b32_e32 v8, 0
	v_mov_b32_e32 v9, 0
	s_waitcnt vmcnt(13)
	v_mov_b32_e32 v10, 0
	v_mov_b32_e32 v11, 0
	v_mov_b32_e32 v12, 0
	v_mov_b32_e32 v13, 0
	s_waitcnt vmcnt(12)
	v_mov_b32_e32 v14, 0
	v_mov_b32_e32 v15, 0
	v_mov_b32_e32 v16, 0
	v_mov_b32_e32 v17, 0
	s_and_saveexec_b64 s[8:9], vcc
	s_cbranch_execz .LBB0_84
	v_ashrrev_i32_e32 v41, 31, v40
	v_lshlrev_b64 v[2:3], 12, v[40:41]
	v_lshlrev_b64 v[40:41], 11, v[40:41]
	v_lshl_add_u64 v[2:3], s[68:69], 0, v[2:3]
	v_lshl_add_u64 v[40:41], s[2:3], 0, v[40:41]
	v_lshl_add_u64 v[14:15], v[2:3], 0, v[0:1]
	v_lshl_add_u64 v[40:41], v[40:41], 0, v[38:39]
	global_load_dwordx4 v[2:5], v[14:15], off
	global_load_dwordx4 v[6:9], v[14:15], off offset:1024
	global_load_dwordx4 v[10:13], v[14:15], off offset:2048
	s_nop 0
	global_load_dwordx4 v[14:17], v[14:15], off offset:3072
	s_nop 0
	global_load_dwordx2 v[86:87], v[40:41], off
	global_load_dwordx2 v[88:89], v[40:41], off offset:512
	global_load_dwordx2 v[90:91], v[40:41], off offset:1024
	global_load_dwordx2 v[92:93], v[40:41], off offset:1536

; DI void phase_ln(const Params& p, int layer, int sub, bool first, bool final_, const u16* M, int glayer, int goff) {
;     ...
;   auto load_row = [&](int row, float4 (&v)[4], u32x2 (&mm)[4]) {
;     const float* xr = first ? xin_row(p, row) : (p.out + (size_t)row * DM);
; #pragma unroll
;     for (int j = 0; j < 4; ++j) {
;       const f32x4v t_ = __builtin_nontemporal_load((const f32x4v*)(xr + j * 256 + lane * 4));
;       v[j] = (float4){t_.x, t_.y, t_.z, t_.w};
;     }
;     if (M) {
; #pragma unroll
;       for (int j = 0; j < 4; ++j) mm[j] = *(const u32x2*)(M + (size_t)row * DM + j * 256 + lane * 4);
;     }
;   };
;     ...
;     if (row + 2 < r1) load_row(row + 2, vn2, mmn2);
.LBB0_86:
	v_add_u32_e32 v148, 2, v82
	v_cmp_lt_i32_e32 vcc, v148, v150
	s_and_saveexec_b64 s[10:11], vcc
	s_cbranch_execz .LBB0_88
	v_ashrrev_i32_e32 v149, 31, v148
	v_lshlrev_b64 v[46:47], 12, v[148:149]
	v_lshlrev_b64 v[84:85], 11, v[148:149]
	v_lshl_add_u64 v[66:67], v[110:111], 0, v[46:47]
	v_lshl_add_u64 v[134:135], v[112:113], 0, v[84:85]
	global_load_dwordx4 v[46:49], v[66:67], off
	global_load_dwordx4 v[54:57], v[66:67], off offset:1024
	global_load_dwordx4 v[62:65], v[66:67], off offset:2048
	s_nop 0
	global_load_dwordx4 v[66:69], v[66:67], off offset:3072
	s_nop 0
	global_load_dwordx2 v[84:85], v[134:135], off
	global_load_dwordx2 v[130:131], v[134:135], off offset:512
	global_load_dwordx2 v[132:133], v[134:135], off offset:1024
	s_nop 0
	global_load_dwordx2 v[134:135], v[134:135], off offset:1536

; DI void phase_ln(const Params& p, int layer, int sub, bool first, bool final_, const u16* M, int glayer, int goff) {
;     ...
;   const int nw = gridDim.x * 8, gw = blockIdx.x * 8 + w;
;   const int rows_per = (NTOK + nw - 1) / nw;
;   const int r0 = gw * rows_per;
;   const int r1 = (r0 + rows_per < NTOK) ? (r0 + rows_per) : NTOK;
;   if (r0 >= r1) return;
;   auto load_row = [&](int row, float4 (&v)[4], u32x2 (&mm)[4]) {
;     const float* xr = first ? xin_row(p, row) : (p.out + (size_t)row * DM);
; #pragma unroll
;     for (int j = 0; j < 4; ++j) {
;       const f32x4v t_ = __builtin_nontemporal_load((const f32x4v*)(xr + j * 256 + lane * 4));
;       v[j] = (float4){t_.x, t_.y, t_.z, t_.w};
;     }
;     if (M) {
; #pragma unroll
;       for (int j = 0; j < 4; ++j) mm[j] = *(const u32x2*)(M + (size_t)row * DM + j * 256 + lane * 4);
;     }
;   };
;   float4 pg[4], psh[4], pgm[4];
;   int cur_bb = -1;
;   float4 v[4], vn[4], vn2[4];
;   u32x2 mm[4], mmn[4], mmn2[4];
; #pragma unroll
;   for (int j = 0; j < 4; ++j) {
;     mm[j] = (u32x2){0u, 0u}; mmn[j] = (u32x2){0u, 0u}; mmn2[j] = (u32x2){0u, 0u};
;     vn[j] = (float4){0.f, 0.f, 0.f, 0.f}; vn2[j] = (float4){0.f, 0.f, 0.f, 0.f};
;   }
;   load_row(r0, v, mm);
;   if (r0 + 1 < r1) load_row(r0 + 1, vn, mmn);
.LBB0_214:
	v_readlane_b32 s16, v253, 9
	s_movk_i32 s98, 0xb00
	s_and_b64 vcc, exec, s[6:7]
	s_mov_b64 s[12:13], s[2:3]
	s_mov_b64 s[14:15], s[90:91]
	v_readlane_b32 s17, v253, 10
	s_cbranch_vccz .LBB0_225
	v_readlane_b32 s6, v255, 6
	s_cmp_gt_i32 s6, 4
	s_mov_b64 s[10:11], -1
	s_cbranch_scc0 .LBB0_238
	v_mov_b32_e32 v40, v204
	s_load_dword s6, s[74:75], 0x0
	s_waitcnt vmcnt(7)
	v_ashrrev_i32_e32 v2, 6, v40
	v_readlane_b32 s8, v253, 14
	s_waitcnt lgkmcnt(0)
	s_lshl_b32 s6, s6, 3
	s_abs_i32 s7, s6
	v_cvt_f32_u32_e32 v0, s7
	s_sub_i32 s9, 0, s7
	v_add_u32_e32 v2, s8, v2
	s_add_i32 s8, s6, 0xbfff
	v_rcp_iflag_f32_e32 v0, v0
	s_xor_b32 s6, s8, s6
	s_abs_i32 s8, s8
	s_ashr_i32 s6, s6, 31
	v_mul_f32_e32 v0, 0x4f7ffffe, v0
	v_cvt_u32_f32_e32 v0, v0
	s_nop 0
	v_readfirstlane_b32 s10, v0
	s_mul_i32 s9, s9, s10
	s_mul_hi_u32 s9, s10, s9
	s_add_i32 s10, s10, s9
	s_mul_hi_u32 s9, s8, s10
	s_mul_i32 s10, s9, s7
	s_sub_i32 s8, s8, s10
	s_add_i32 s11, s9, 1
	s_sub_i32 s10, s8, s7
	s_cmp_ge_u32 s8, s7
	s_cselect_b32 s9, s11, s9
	s_cselect_b32 s8, s10, s8
	s_add_i32 s10, s9, 1
	s_cmp_ge_u32 s8, s7
	s_cselect_b32 s7, s10, s9
	s_xor_b32 s7, s7, s6
	s_sub_i32 s6, s7, s6
	v_mul_lo_u32 v82, s6, v2
	v_add_u32_e32 v0, s6, v82
	v_min_i32_e32 v148, 0xc000, v0
	v_cmp_lt_i32_e32 vcc, v82, v148
	s_and_saveexec_b64 s[6:7], vcc
	v_readlane_b32 s16, v254, 52
	v_readlane_b32 s17, v254, 53
	v_readlane_b32 s18, v254, 54
	v_readlane_b32 s19, v254, 55
	s_mov_b64 s[14:15], 0x800
	v_readlane_b32 s20, v254, 56
	v_readlane_b32 s21, v254, 57
	v_readlane_b32 s22, v254, 58
	v_readlane_b32 s23, v254, 59
	v_readlane_b32 s24, v254, 60
	v_readlane_b32 s25, v254, 61
	v_readlane_b32 s26, v254, 62
	v_readlane_b32 s27, v254, 63
	v_readlane_b32 s28, v255, 0
	v_readlane_b32 s29, v255, 1
	v_readlane_b32 s30, v255, 2
	v_readlane_b32 s31, v255, 3
	s_cbranch_execz .LBB0_237
	v_add_u32_e32 v0, 0xffff8000, v82
	v_cmp_gt_i32_e32 vcc, s48, v82
	v_mov_b32_e32 v4, s17
	v_ashrrev_i32_e32 v83, 31, v82
	v_cndmask_b32_e32 v2, v0, v82, vcc
	v_mov_b32_e32 v0, s19
	v_cndmask_b32_e32 v5, v0, v4, vcc
	v_mov_b32_e32 v0, s18
	v_mov_b32_e32 v4, s16
	v_cndmask_b32_e32 v3, 0, v83, vcc
	v_cndmask_b32_e32 v4, v0, v4, vcc
	v_lshlrev_b32_e32 v0, 2, v40
	v_lshlrev_b64 v[2:3], 12, v[2:3]
	v_and_b32_e32 v41, 0xfc, v0
	v_lshl_add_u64 v[2:3], v[4:5], 0, v[2:3]
	v_lshlrev_b32_e32 v0, 2, v41
	v_lshl_add_u64 v[2:3], v[2:3], 0, v[0:1]
	v_lshlrev_b64 v[34:35], 11, v[82:83]
	global_load_dwordx4 v[30:33], v[2:3], off
	global_load_dwordx4 v[26:29], v[2:3], off offset:1024
	global_load_dwordx4 v[22:25], v[2:3], off offset:2048
	global_load_dwordx4 v[18:21], v[2:3], off offset:3072
	v_lshl_add_u64 v[2:3], s[2:3], 0, v[34:35]
	v_lshlrev_b32_e32 v36, 1, v41
	v_mov_b32_e32 v37, v1
	v_lshl_add_u64 v[2:3], v[2:3], 0, v[36:37]
	global_load_dwordx2 v[108:109], v[2:3], off
	global_load_dwordx2 v[106:107], v[2:3], off offset:512
	global_load_dwordx2 v[100:101], v[2:3], off offset:1024
	global_load_dwordx2 v[94:95], v[2:3], off offset:1536
	v_add_u32_e32 v38, 1, v82
	v_cmp_lt_i32_e32 vcc, v38, v148
	v_mov_b32_e32 v2, 0
	v_mov_b32_e32 v84, 0
	v_mov_b32_e32 v86, 0
	v_mov_b32_e32 v87, 0
	v_mov_b32_e32 v88, 0
	v_mov_b32_e32 v89, 0
	v_mov_b32_e32 v90, 0
	v_mov_b32_e32 v91, 0
	v_mov_b32_e32 v92, 0
	v_mov_b32_e32 v93, 0
	v_mov_b32_e32 v3, 0
	v_mov_b32_e32 v4, 0
	v_mov_b32_e32 v5, 0
	s_waitcnt vmcnt(14)
	v_mov_b32_e32 v6, 0
	v_mov_b32_e32 v7, 0
	v_mov_b32_e32 v8, 0
	v_mov_b32_e32 v9, 0
	s_waitcnt vmcnt(13)
	v_mov_b32_e32 v10, 0
	v_mov_b32_e32 v11, 0
	v_mov_b32_e32 v12, 0
	v_mov_b32_e32 v13, 0
	s_waitcnt vmcnt(12)
	v_mov_b32_e32 v14, 0
	v_mov_b32_e32 v15, 0
	v_mov_b32_e32 v16, 0
	v_mov_b32_e32 v17, 0
	s_and_saveexec_b64 s[8:9], vcc
	s_cbranch_execz .LBB0_219
	s_movk_i32 s10, 0x7fff
	v_add_u32_e32 v2, 0xffff8001, v82
	v_ashrrev_i32_e32 v39, 31, v38
	v_cmp_gt_i32_e32 vcc, s10, v82
	v_mov_b32_e32 v4, s19
	v_mov_b32_e32 v5, s17
	v_cndmask_b32_e32 v3, 0, v39, vcc
	v_cndmask_b32_e32 v2, v2, v38, vcc
	v_cndmask_b32_e32 v5, v4, v5, vcc
	v_mov_b32_e32 v4, s18
	v_mov_b32_e32 v6, s16
	v_cndmask_b32_e32 v4, v4, v6, vcc
	v_lshlrev_b64 v[2:3], 12, v[2:3]
	v_lshlrev_b64 v[38:39], 11, v[38:39]
	v_lshl_add_u64 v[2:3], v[4:5], 0, v[2:3]
	v_lshl_add_u64 v[38:39], s[2:3], 0, v[38:39]
	v_lshl_add_u64 v[14:15], v[2:3], 0, v[0:1]
	v_lshl_add_u64 v[38:39], v[38:39], 0, v[36:37]
	global_load_dwordx4 v[2:5], v[14:15], off
	global_load_dwordx4 v[6:9], v[14:15], off offset:1024
	global_load_dwordx4 v[10:13], v[14:15], off offset:2048
	s_nop 0
	global_load_dwordx4 v[14:17], v[14:15], off offset:3072
	s_nop 0
	global_load_dwordx2 v[86:87], v[38:39], off
	global_load_dwordx2 v[88:89], v[38:39], off offset:512
	global_load_dwordx2 v[90:91], v[38:39], off offset:1024
	global_load_dwordx2 v[92:93], v[38:39], off offset:1536

; DI void phase_ln(const Params& p, int layer, int sub, bool first, bool final_, const u16* M, int glayer, int goff) {
;     ...
;   auto load_row = [&](int row, float4 (&v)[4], u32x2 (&mm)[4]) {
;     const float* xr = first ? xin_row(p, row) : (p.out + (size_t)row * DM);
; #pragma unroll
;     for (int j = 0; j < 4; ++j) {
;       const f32x4v t_ = __builtin_nontemporal_load((const f32x4v*)(xr + j * 256 + lane * 4));
;       v[j] = (float4){t_.x, t_.y, t_.z, t_.w};
;     }
;     if (M) {
; #pragma unroll
;       for (int j = 0; j < 4; ++j) mm[j] = *(const u32x2*)(M + (size_t)row * DM + j * 256 + lane * 4);
;     }
;   };
;     ...
;     if (row + 2 < r1) load_row(row + 2, vn2, mmn2);
.LBB0_221:
	v_add_u32_e32 v146, 2, v82
	v_cmp_lt_i32_e32 vcc, v146, v148
	s_and_saveexec_b64 s[10:11], vcc
	s_cbranch_execz .LBB0_223
	s_movk_i32 s12, 0x7ffe
	v_add_u32_e32 v50, 0xffff8002, v82
	v_ashrrev_i32_e32 v147, 31, v146
	v_cmp_gt_i32_e32 vcc, s12, v82
	v_mov_b32_e32 v52, s19
	v_mov_b32_e32 v53, s17
	v_cndmask_b32_e32 v51, 0, v147, vcc
	v_cndmask_b32_e32 v50, v50, v146, vcc
	v_cndmask_b32_e32 v53, v52, v53, vcc
	v_mov_b32_e32 v52, s18
	v_mov_b32_e32 v58, s16
	v_cndmask_b32_e32 v52, v52, v58, vcc
	v_lshlrev_b64 v[50:51], 12, v[50:51]
	v_lshl_add_u64 v[50:51], v[52:53], 0, v[50:51]
	v_lshlrev_b64 v[84:85], 11, v[146:147]
	v_lshl_add_u64 v[70:71], v[50:51], 0, v[0:1]
	v_lshl_add_u64 v[136:137], v[110:111], 0, v[84:85]
	global_load_dwordx4 v[50:53], v[70:71], off
	global_load_dwordx4 v[58:61], v[70:71], off offset:1024
	global_load_dwordx4 v[62:65], v[70:71], off offset:2048
	s_nop 0
	global_load_dwordx4 v[70:73], v[70:71], off offset:3072
	s_nop 0
	global_load_dwordx2 v[84:85], v[136:137], off
	global_load_dwordx2 v[132:133], v[136:137], off offset:512
	global_load_dwordx2 v[134:135], v[136:137], off offset:1024
	s_nop 0
	global_load_dwordx2 v[136:137], v[136:137], off offset:1536

; DI void phase_ln(const Params& p, int layer, int sub, bool first, bool final_, const u16* M, int glayer, int goff) {
;     ...
;   const int nw = gridDim.x * 8, gw = blockIdx.x * 8 + w;
;   const int rows_per = (NTOK + nw - 1) / nw;
;   const int r0 = gw * rows_per;
;   const int r1 = (r0 + rows_per < NTOK) ? (r0 + rows_per) : NTOK;
;   if (r0 >= r1) return;
;   auto load_row = [&](int row, float4 (&v)[4], u32x2 (&mm)[4]) {
;     const float* xr = first ? xin_row(p, row) : (p.out + (size_t)row * DM);
; #pragma unroll
;     for (int j = 0; j < 4; ++j) {
;       const f32x4v t_ = __builtin_nontemporal_load((const f32x4v*)(xr + j * 256 + lane * 4));
;       v[j] = (float4){t_.x, t_.y, t_.z, t_.w};
;     }
;     if (M) {
; #pragma unroll
;       for (int j = 0; j < 4; ++j) mm[j] = *(const u32x2*)(M + (size_t)row * DM + j * 256 + lane * 4);
;     }
;   };
;   float4 pg[4], psh[4], pgm[4];
;   int cur_bb = -1;
;   float4 v[4], vn[4], vn2[4];
;   u32x2 mm[4], mmn[4], mmn2[4];
; #pragma unroll
;   for (int j = 0; j < 4; ++j) {
;     mm[j] = (u32x2){0u, 0u}; mmn[j] = (u32x2){0u, 0u}; mmn2[j] = (u32x2){0u, 0u};
;     vn[j] = (float4){0.f, 0.f, 0.f, 0.f}; vn2[j] = (float4){0.f, 0.f, 0.f, 0.f};
;   }
;   load_row(r0, v, mm);
;   if (r0 + 1 < r1) load_row(r0 + 1, vn, mmn);
.LBB0_227:
	s_and_b64 vcc, exec, s[6:7]
	s_cbranch_vccz .LBB0_240
	v_mov_b32_e32 v42, v204
	s_load_dword s6, s[74:75], 0x0
	s_mov_b64 s[14:15], s[10:11]
	s_waitcnt vmcnt(7)
	v_ashrrev_i32_e32 v2, 6, v42
	v_readlane_b32 s8, v253, 14
	s_waitcnt lgkmcnt(0)
	s_lshl_b32 s6, s6, 3
	s_abs_i32 s7, s6
	v_cvt_f32_u32_e32 v0, s7
	s_sub_i32 s9, 0, s7
	v_add_u32_e32 v2, s8, v2
	s_add_i32 s8, s6, 0xbfff
	v_rcp_iflag_f32_e32 v0, v0
	s_xor_b32 s6, s8, s6
	s_abs_i32 s8, s8
	s_ashr_i32 s6, s6, 31
	v_mul_f32_e32 v0, 0x4f7ffffe, v0
	v_cvt_u32_f32_e32 v0, v0
	s_nop 0
	v_readfirstlane_b32 s10, v0
	s_mul_i32 s9, s9, s10
	s_mul_hi_u32 s9, s10, s9
	s_add_i32 s10, s10, s9
	s_mul_hi_u32 s9, s8, s10
	s_mul_i32 s10, s9, s7
	s_sub_i32 s8, s8, s10
	s_add_i32 s11, s9, 1
	s_sub_i32 s10, s8, s7
	s_cmp_ge_u32 s8, s7
	s_cselect_b32 s9, s11, s9
	s_cselect_b32 s8, s10, s8
	s_add_i32 s10, s9, 1
	s_cmp_ge_u32 s8, s7
	s_cselect_b32 s7, s10, s9
	s_xor_b32 s7, s7, s6
	s_sub_i32 s6, s7, s6
	v_mul_lo_u32 v82, s6, v2
	v_add_u32_e32 v0, s6, v82
	v_min_i32_e32 v150, 0xc000, v0
	v_cmp_lt_i32_e32 vcc, v82, v150
	s_and_saveexec_b64 s[6:7], vcc
	s_cbranch_execz .LBB0_239
	v_ashrrev_i32_e32 v83, 31, v82
	v_lshlrev_b32_e32 v0, 2, v42
	v_lshlrev_b64 v[34:35], 12, v[82:83]
	v_and_b32_e32 v43, 0xfc, v0
	v_lshl_add_u64 v[2:3], s[68:69], 0, v[34:35]
	v_lshlrev_b32_e32 v0, 2, v43
	v_lshl_add_u64 v[2:3], v[2:3], 0, v[0:1]
	v_lshlrev_b64 v[36:37], 11, v[82:83]
	global_load_dwordx4 v[30:33], v[2:3], off
	global_load_dwordx4 v[26:29], v[2:3], off offset:1024
	global_load_dwordx4 v[22:25], v[2:3], off offset:2048
	global_load_dwordx4 v[18:21], v[2:3], off offset:3072
	v_lshl_add_u64 v[2:3], s[90:91], 0, v[36:37]
	v_lshlrev_b32_e32 v38, 1, v43
	v_mov_b32_e32 v39, v1
	v_lshl_add_u64 v[2:3], v[2:3], 0, v[38:39]
	global_load_dwordx2 v[108:109], v[2:3], off
	global_load_dwordx2 v[106:107], v[2:3], off offset:512
	global_load_dwordx2 v[104:105], v[2:3], off offset:1024
	global_load_dwordx2 v[98:99], v[2:3], off offset:1536
	v_add_u32_e32 v40, 1, v82
	v_cmp_lt_i32_e32 vcc, v40, v150
	v_mov_b32_e32 v2, 0
	v_mov_b32_e32 v84, 0
	v_mov_b32_e32 v86, 0
	v_mov_b32_e32 v87, 0
	v_mov_b32_e32 v88, 0
	v_mov_b32_e32 v89, 0
	v_mov_b32_e32 v90, 0
	v_mov_b32_e32 v91, 0
	v_mov_b32_e32 v92, 0
	v_mov_b32_e32 v93, 0
	v_mov_b32_e32 v3, 0
	v_mov_b32_e32 v4, 0
	v_mov_b32_e32 v5, 0
	s_waitcnt vmcnt(14)
	v_mov_b32_e32 v6, 0
	v_mov_b32_e32 v7, 0
	v_mov_b32_e32 v8, 0
	v_mov_b32_e32 v9, 0
	s_waitcnt vmcnt(13)
	v_mov_b32_e32 v10, 0
	v_mov_b32_e32 v11, 0
	v_mov_b32_e32 v12, 0
	v_mov_b32_e32 v13, 0
	s_waitcnt vmcnt(12)
	v_mov_b32_e32 v14, 0
	v_mov_b32_e32 v15, 0
	v_mov_b32_e32 v16, 0
	v_mov_b32_e32 v17, 0
	s_and_saveexec_b64 s[8:9], vcc
	s_cbranch_execz .LBB0_231
	v_ashrrev_i32_e32 v41, 31, v40
	v_lshlrev_b64 v[2:3], 12, v[40:41]
	v_lshlrev_b64 v[40:41], 11, v[40:41]
	v_lshl_add_u64 v[2:3], s[68:69], 0, v[2:3]
	v_lshl_add_u64 v[40:41], s[90:91], 0, v[40:41]
	v_lshl_add_u64 v[14:15], v[2:3], 0, v[0:1]
	v_lshl_add_u64 v[40:41], v[40:41], 0, v[38:39]
	global_load_dwordx4 v[2:5], v[14:15], off
	global_load_dwordx4 v[6:9], v[14:15], off offset:1024
	global_load_dwordx4 v[10:13], v[14:15], off offset:2048
	s_nop 0
	global_load_dwordx4 v[14:17], v[14:15], off offset:3072
	s_nop 0
	global_load_dwordx2 v[86:87], v[40:41], off
	global_load_dwordx2 v[88:89], v[40:41], off offset:512
	global_load_dwordx2 v[90:91], v[40:41], off offset:1024
	global_load_dwordx2 v[92:93], v[40:41], off offset:1536

; DI int opaque_tid() { int t = threadIdx.x; asm volatile("" : "+v"(t)); return t; }
; template <bool SWAP>
; DI void gemm_mainloop(f32x16 (&acc)[4][2], const u16* __restrict__ A, int lda, int rlo, int rhi,
;                       const u16* __restrict__ B, int ldb, int K, char* lds, const u16* zero_line) {
;   const int tid = opaque_tid(), lane = tid & 63, w = tid >> 6;
;   const int wm = w >> 2, wn = w & 3;
;   const int h = lane >> 5, r = lane & 31;
;   const int lr = tid >> 3, lc = tid & 7;
; #pragma unroll
;   for (int mi = 0; mi < 4; ++mi)
; #pragma unroll
;     for (int ni = 0; ni < 2; ++ni)
; #pragma unroll
;       for (int i = 0; i < 16; ++i) acc[mi][ni][i] = 0.f;
;   const int gch = (lc ^ ((lr >> 1) & 7)) * 8;
;   const u16* ap = A + (ptrdiff_t)lr * lda + gch;
;   const u16* bp = B + (ptrdiff_t)lr * ldb + gch;
;   const int nk = K >> 6;
;   typedef __attribute__((address_space(3))) unsigned lds_u32;
;   auto glds = [&](int kt, int st) {
;     char* as_ = lds + st * 65536 + tid * 16;
; #pragma unroll
;     for (int i = 0; i < 4; ++i) {
;       const int rr = lr + 64 * i;
;       const u16* srca = (rr >= rlo && rr < rhi) ? (ap + (ptrdiff_t)(64 * i) * lda + kt * 64) : (zero_line + lc * 8);
;       __builtin_amdgcn_global_load_lds((const unsigned*)srca, (lds_u32*)(as_ + i * 8192), 16, 0, 0);
;       __builtin_amdgcn_global_load_lds((const unsigned*)(bp + (ptrdiff_t)(64 * i) * ldb + kt * 64), (lds_u32*)(as_ + 32768 + i * 8192), 16, 0, 0);
;     }
;   };
;   const int sw = (r >> 1) & 7;
;   const int arow_off = (wm * 128 + r) * 128;
;   const int brow_off = 32768 + (wn * 64 + r) * 128;
; template <int EPI>
; DI void phase_gemm(const Params& p, const GemmArgs& ga, char* lds) {
;     ...
;   for (int it = 0; it * (int)gridDim.x < total; ++it) {
;     const int lt = logical_index(it);
;     if (lt >= total) continue;
;     int mt, nt;
;     tile_mn(lt, Mt, ga.Nt, mt, nt);
;     int bb, tokbase, S, pos0, rlo = 0, rhi = 256;
;     if (EPI == EPI_UP) {
;       bb = 0; tokbase = 0; S = NTOK;
;       pos0 = 254 * mt - 1;
;       rlo = (mt == 0) ? 1 : 0;
;       rhi = NTOK - pos0; if (rhi > 256) rhi = 256;
;     } else {
;       seq_of_token(mt * 256, bb, tokbase, S);
;       pos0 = mt * 256 - tokbase;
;     }
;     const u16* A = ga.A + (ptrdiff_t)(tokbase + pos0) * ga.lda;
;     const u16* B = ga.Bt + (size_t)(nt * 256) * ga.K;
.LBB0_244:
	s_add_i32 s6, s6, s27
	s_cmpk_gt_i32 s6, 0x2ff
	s_cbranch_scc1 .LBB0_243
	s_ashr_i32 s7, s6, 31
	s_lshr_b32 s7, s7, 27
	s_add_i32 s7, s6, s7
	s_ashr_i32 s35, s7, 5
	s_andn2_b32 s7, s7, 31
	s_sub_i32 s6, s6, s7
	s_ashr_i32 s7, s6, 31
	s_lshr_b32 s7, s7, 29
	s_add_i32 s7, s6, s7
	s_ashr_i32 s7, s7, 3
	s_lshl_b32 s8, s35, 11
	s_lshl_b32 s6, s6, 8
	s_lshl_b32 s24, s7, 8
	s_add_i32 s6, s6, s8
	s_lshl_b32 s36, s7, 11
	s_ashr_i32 s25, s24, 31
	s_sub_i32 s34, s6, s36
	s_mul_i32 s6, s25, s98
	s_mul_hi_u32 s7, s24, s98
	s_add_i32 s7, s7, s6
	s_mul_i32 s6, s24, s98
	s_lshl_b64 s[6:7], s[6:7], 1
	s_add_u32 s6, s16, s6
	v_mov_b32_e32 v10, v204
	s_addc_u32 s7, s17, s7
	s_ashr_i32 s8, s34, 31
	s_mul_i32 s8, s8, s98
	v_ashrrev_i32_e32 v2, 3, v10
	s_mul_hi_u32 s9, s34, s98
	v_mad_u64_u32 v[4:5], s[10:11], v2, s98, 0
	s_add_i32 s9, s9, s8
	s_mul_i32 s8, s34, s98
	v_ashrrev_i32_e32 v3, 31, v2
	v_mov_b32_e32 v0, v5
	s_lshl_b64 s[8:9], s[8:9], 1
	v_lshrrev_b32_e32 v12, 1, v2
	v_mad_u64_u32 v[6:7], s[10:11], v3, s98, v[0:1]
	s_add_u32 s8, s12, s8
	v_xor_b32_e32 v9, v12, v10
	v_mov_b32_e32 v5, v6
	s_addc_u32 s9, s13, s9
	v_lshlrev_b64 v[4:5], 1, v[4:5]
	v_lshlrev_b32_e32 v0, 4, v9
	v_and_b32_e32 v8, 31, v10
	v_lshl_add_u64 v[6:7], s[8:9], 0, v[4:5]
	v_and_b32_e32 v0, 0x70, v0
	v_lshl_add_u64 v[4:5], s[6:7], 0, v[4:5]
	v_lshrrev_b32_e32 v13, 1, v10
	v_lshl_add_u64 v[6:7], v[6:7], 0, v[0:1]
	v_lshl_add_u64 v[4:5], v[4:5], 0, v[0:1]
	v_and_or_b32 v0, v13, s51, v8
	v_lshlrev_b32_e32 v203, 7, v0
	v_lshlrev_b32_e32 v0, 7, v10
	v_lshlrev_b32_e32 v226, 4, v10
	v_and_b32_e32 v202, 0x6f80, v0
	v_and_b32_e32 v0, 0x70, v226
	v_add_u32_e32 v15, 0x8000, v226
	v_lshl_add_u64 v[180:181], s[80:81], 0, v[0:1]
	v_cmp_gt_u32_e32 vcc, s50, v2
	v_readfirstlane_b32 s6, v226
	s_mov_b32 m0, s6
	v_cndmask_b32_e32 v9, v181, v7, vcc
	v_cndmask_b32_e32 v8, v180, v6, vcc
	v_readfirstlane_b32 s6, v15
	v_add_u32_e32 v0, 64, v2
	s_barrier
	s_mov_b32 m0, s6
	v_cmp_gt_u32_e64 s[6:7], s50, v0
	v_add_u32_e32 v0, 0x2000, v226
	v_lshl_add_u64 v[6:7], v[6:7], 0, s[18:19]
	v_readfirstlane_b32 s8, v0
	v_add_u32_e32 v0, 0xa000, v226
	v_cndmask_b32_e64 v9, v181, v7, s[6:7]
	v_cndmask_b32_e64 v8, v180, v6, s[6:7]
	s_mov_b32 m0, s8
	v_readfirstlane_b32 s8, v0
	v_add_u32_e32 v0, 0x80, v2
	s_mov_b32 m0, s8
	v_cmp_gt_u32_e64 s[8:9], s50, v0
	v_add_u32_e32 v0, 0x4000, v226
	v_lshl_add_u64 v[4:5], v[4:5], 0, s[18:19]
	v_lshl_add_u64 v[6:7], v[6:7], 0, s[18:19]
	v_readfirstlane_b32 s10, v0
	v_add_u32_e32 v0, 0xc000, v226
	v_cndmask_b32_e64 v9, v181, v7, s[8:9]
	v_cndmask_b32_e64 v8, v180, v6, s[8:9]
	s_mov_b32 m0, s10
	v_readfirstlane_b32 s10, v0
	v_add_u32_e32 v0, 0xc0, v2
	s_mov_b32 m0, s10
	v_cmp_gt_u32_e64 s[10:11], s50, v0
	v_add_u32_e32 v0, 0x6000, v226
	v_lshl_add_u64 v[4:5], v[4:5], 0, s[18:19]
	v_lshl_add_u64 v[6:7], v[6:7], 0, s[18:19]
	v_readfirstlane_b32 s37, v0
	v_add_u32_e32 v0, 0xe000, v226
	v_cndmask_b32_e64 v7, v181, v7, s[10:11]
	v_cndmask_b32_e64 v6, v180, v6, s[10:11]
	s_mov_b32 m0, s37
	v_readfirstlane_b32 s37, v0
	v_lshl_add_u64 v[4:5], v[4:5], 0, s[18:19]
	s_mov_b32 m0, s37
	s_sub_i32 s36, s29, s36
	s_mulk_i32 s35, 0x1800
	s_sub_i32 s36, s36, s35
	s_ashr_i32 s37, s36, 31
	v_lshlrev_b64 v[2:3], 1, v[2:3]
	s_lshl_b64 s[36:37], s[36:37], 1
	v_lshl_add_u64 v[4:5], v[2:3], 0, s[36:37]
	v_mov_b64_e32 v[6:7], s[20:21]
	v_mad_u64_u32 v[182:183], s[38:39], s98, v4, v[6:7]
	v_mov_b32_e32 v4, v183
	v_mad_u64_u32 v[4:5], s[38:39], s98, v5, v[4:5]
	s_lshl_b64 s[38:39], s[24:25], 1
	v_bfe_u32 v11, v10, 5, 1
	v_mov_b32_e32 v183, v4
	v_lshl_add_u64 v[4:5], v[2:3], 0, s[38:39]
	v_mov_b64_e32 v[8:9], s[22:23]
	v_bfe_u32 v14, v10, 1, 3
	v_bitop3_b32 v0, v13, v11, 7 bitop3:0x6c
	v_mad_u64_u32 v[186:187], s[40:41], s98, v4, v[8:9]
	v_lshlrev_b32_e32 v228, 4, v0
	v_bitop3_b32 v0, v11, v14, 2 bitop3:0x36
	v_mov_b32_e32 v4, v187
	v_lshlrev_b32_e32 v227, 4, v0
	v_bitop3_b32 v0, v11, v14, 4 bitop3:0x36
	v_mad_u64_u32 v[4:5], s[40:41], s98, v5, v[4:5]
	v_lshlrev_b32_e32 v201, 4, v0
	v_bitop3_b32 v0, v11, v14, 6 bitop3:0x36
	v_mov_b32_e32 v187, v4
	v_lshl_add_u64 v[4:5], v[2:3], 0, s[4:5]
	v_lshlrev_b32_e32 v179, 4, v0
	v_bitop3_b32 v0, v12, 7, v10 bitop3:0x48
	v_lshl_add_u64 v[10:11], v[4:5], 0, s[36:37]
	v_lshl_add_u64 v[4:5], v[4:5], 0, s[38:39]
	v_mad_u64_u32 v[188:189], s[40:41], s98, v10, v[6:7]
	v_mad_u64_u32 v[190:191], s[40:41], s98, v4, v[8:9]
	v_mov_b32_e32 v10, v189
	v_mov_b32_e32 v4, v191
	v_mad_u64_u32 v[10:11], s[40:41], s98, v11, v[10:11]
	v_mad_u64_u32 v[4:5], s[40:41], s98, v5, v[4:5]
	s_mov_b64 s[40:41], 0x100
	v_mov_b32_e32 v191, v4
	v_lshl_add_u64 v[4:5], v[2:3], 0, s[40:41]
	v_mov_b32_e32 v189, v10
	v_lshl_add_u64 v[10:11], v[4:5], 0, s[36:37]
	v_lshl_add_u64 v[4:5], v[4:5], 0, s[38:39]
	v_mad_u64_u32 v[192:193], s[40:41], s98, v10, v[6:7]
	v_mad_u64_u32 v[194:195], s[40:41], s98, v4, v[8:9]
	v_mov_b32_e32 v10, v193
	v_mov_b32_e32 v4, v195
	v_mad_u64_u32 v[10:11], s[40:41], s98, v11, v[10:11]
	v_mad_u64_u32 v[4:5], s[40:41], s98, v5, v[4:5]
	s_mov_b64 s[40:41], 0x180
	s_nop 0
	v_lshl_add_u64 v[2:3], v[2:3], 0, s[40:41]
	v_mov_b32_e32 v195, v4
	v_lshl_add_u64 v[4:5], v[2:3], 0, s[36:37]
	v_lshl_add_u64 v[2:3], v[2:3], 0, s[38:39]
	v_mad_u64_u32 v[198:199], s[36:37], s98, v2, v[8:9]
	v_mad_u64_u32 v[196:197], s[36:37], s98, v4, v[6:7]
	v_mov_b32_e32 v2, v199
	s_waitcnt vmcnt(0)
; template <bool SWAP>
; DI void gemm_mainloop(f32x16 (&acc)[4][2], const u16* __restrict__ A, int lda, int rlo, int rhi,
;                       const u16* __restrict__ B, int ldb, int K, char* lds, const u16* zero_line) {
;     ...
; #pragma unroll
;   for (int mi = 0; mi < 4; ++mi)
; #pragma unroll
;     for (int ni = 0; ni < 2; ++ni)
; #pragma unroll
;       for (int i = 0; i < 16; ++i) acc[mi][ni][i] = 0.f;
;   const int gch = (lc ^ ((lr >> 1) & 7)) * 8;
;   const u16* ap = A + (ptrdiff_t)lr * lda + gch;
;   const u16* bp = B + (ptrdiff_t)lr * ldb + gch;
;   const int nk = K >> 6;
;   typedef __attribute__((address_space(3))) unsigned lds_u32;
;   auto glds = [&](int kt, int st) {
;     char* as_ = lds + st * 65536 + tid * 16;
; #pragma unroll
;     for (int i = 0; i < 4; ++i) {
;       const int rr = lr + 64 * i;
;       const u16* srca = (rr >= rlo && rr < rhi) ? (ap + (ptrdiff_t)(64 * i) * lda + kt * 64) : (zero_line + lc * 8);
;       __builtin_amdgcn_global_load_lds((const unsigned*)srca, (lds_u32*)(as_ + i * 8192), 16, 0, 0);
;       __builtin_amdgcn_global_load_lds((const unsigned*)(bp + (ptrdiff_t)(64 * i) * ldb + kt * 64), (lds_u32*)(as_ + 32768 + i * 8192), 16, 0, 0);
;     }
;   };
;   const int sw = (r >> 1) & 7;
;   const int arow_off = (wm * 128 + r) * 128;
;   const int brow_off = 32768 + (wn * 64 + r) * 128;
;   __syncthreads();
;   glds(0, 0);
;   asm volatile("s_waitcnt vmcnt(0)" ::: "memory");
;   __syncthreads();
	v_mov_b32_e32 v4, v197
	v_mad_u64_u32 v[2:3], s[36:37], s98, v3, v[2:3]
	v_mad_u64_u32 v[4:5], s[36:37], s98, v5, v[4:5]
	v_mov_b32_e32 v199, v2
	v_mov_b32_e32 v130, 0
	v_mov_b32_e32 v2, 0
	v_lshlrev_b32_e32 v0, 4, v0
	v_mov_b32_e32 v193, v10
	v_mov_b32_e32 v197, v4
	s_mov_b32 s25, 0x10000
	v_mov_b32_e32 v3, v2
	v_mov_b32_e32 v4, v2
	v_mov_b32_e32 v5, v2
	v_mov_b32_e32 v6, v2
	v_mov_b32_e32 v7, v2
	v_mov_b32_e32 v8, v2
	v_mov_b32_e32 v9, v2
	v_mov_b32_e32 v10, v2
	v_mov_b32_e32 v11, v2
	v_mov_b32_e32 v12, v2
	v_mov_b32_e32 v13, v2
	v_mov_b32_e32 v14, v2
	v_mov_b32_e32 v15, v2
	v_mov_b32_e32 v16, v2
	v_mov_b32_e32 v17, v2
	v_mov_b32_e32 v18, v2
	v_mov_b32_e32 v19, v2
	v_mov_b32_e32 v20, v2
	v_mov_b32_e32 v21, v2
	v_mov_b32_e32 v22, v2
	v_mov_b32_e32 v23, v2
	v_mov_b32_e32 v24, v2
	v_mov_b32_e32 v25, v2
	v_mov_b32_e32 v26, v2
	v_mov_b32_e32 v27, v2
	v_mov_b32_e32 v28, v2
	v_mov_b32_e32 v29, v2
	v_mov_b32_e32 v30, v2
	v_mov_b32_e32 v31, v2
	v_mov_b32_e32 v32, v2
	v_mov_b32_e32 v33, v2
	v_mov_b32_e32 v34, v2
	v_mov_b32_e32 v35, v2
	v_mov_b32_e32 v36, v2
	v_mov_b32_e32 v37, v2
	v_mov_b32_e32 v38, v2
	v_mov_b32_e32 v39, v2
	v_mov_b32_e32 v40, v2
	v_mov_b32_e32 v41, v2
	v_mov_b32_e32 v42, v2
	v_mov_b32_e32 v43, v2
	v_mov_b32_e32 v44, v2
	v_mov_b32_e32 v45, v2
	v_mov_b32_e32 v46, v2
	v_mov_b32_e32 v47, v2
	v_mov_b32_e32 v48, v2
	v_mov_b32_e32 v49, v2
	v_mov_b32_e32 v50, v2
	v_mov_b32_e32 v51, v2
	v_mov_b32_e32 v52, v2
	v_mov_b32_e32 v53, v2
	v_mov_b32_e32 v54, v2
	v_mov_b32_e32 v55, v2
	v_mov_b32_e32 v56, v2
	v_mov_b32_e32 v57, v2
	v_mov_b32_e32 v58, v2
	v_mov_b32_e32 v59, v2
	v_mov_b32_e32 v60, v2
	v_mov_b32_e32 v61, v2
	v_mov_b32_e32 v62, v2
	v_mov_b32_e32 v63, v2
	v_mov_b32_e32 v64, v2
	v_mov_b32_e32 v65, v2
	v_mov_b32_e32 v66, v2
	v_mov_b32_e32 v67, v2
	v_mov_b32_e32 v68, v2
	v_mov_b32_e32 v69, v2
	v_mov_b32_e32 v70, v2
	v_mov_b32_e32 v71, v2
	v_mov_b32_e32 v72, v2
	v_mov_b32_e32 v73, v2
	v_mov_b32_e32 v74, v2
	v_mov_b32_e32 v75, v2
	v_mov_b32_e32 v76, v2
	v_mov_b32_e32 v77, v2
	v_mov_b32_e32 v78, v2
	v_mov_b32_e32 v79, v2
	v_mov_b32_e32 v80, v2
	v_mov_b32_e32 v81, v2
	v_mov_b32_e32 v82, v2
	v_mov_b32_e32 v83, v2
	v_mov_b32_e32 v84, v2
	v_mov_b32_e32 v85, v2
	v_mov_b32_e32 v86, v2
	v_mov_b32_e32 v87, v2
	v_mov_b32_e32 v88, v2
	v_mov_b32_e32 v89, v2
	v_mov_b32_e32 v90, v2
	v_mov_b32_e32 v91, v2
	v_mov_b32_e32 v92, v2
	v_mov_b32_e32 v93, v2
	v_mov_b32_e32 v94, v2
	v_mov_b32_e32 v95, v2
	v_mov_b32_e32 v96, v2
	v_mov_b32_e32 v97, v2
	v_mov_b32_e32 v98, v2
	v_mov_b32_e32 v99, v2
	v_mov_b32_e32 v100, v2
	v_mov_b32_e32 v101, v2
	v_mov_b32_e32 v102, v2
	v_mov_b32_e32 v103, v2
	v_mov_b32_e32 v104, v2
	v_mov_b32_e32 v105, v2
	v_mov_b32_e32 v106, v2
	v_mov_b32_e32 v107, v2
	v_mov_b32_e32 v108, v2
	v_mov_b32_e32 v109, v2
	v_mov_b32_e32 v110, v2
	v_mov_b32_e32 v111, v2
	v_mov_b32_e32 v112, v2
	v_mov_b32_e32 v113, v2
	v_mov_b32_e32 v114, v2
	v_mov_b32_e32 v115, v2
	v_mov_b32_e32 v116, v2
	v_mov_b32_e32 v117, v2
	v_mov_b32_e32 v118, v2
	v_mov_b32_e32 v119, v2
	v_mov_b32_e32 v120, v2
	v_mov_b32_e32 v121, v2
	v_mov_b32_e32 v122, v2
	v_mov_b32_e32 v123, v2
	v_mov_b32_e32 v124, v2
	v_mov_b32_e32 v125, v2
	v_mov_b32_e32 v126, v2
	v_mov_b32_e32 v127, v2
	v_mov_b32_e32 v128, v2
	v_mov_b32_e32 v129, v2
	v_mov_b32_e32 v131, v130
	v_mov_b32_e32 v132, v130
	v_mov_b32_e32 v133, v130
	v_mov_b32_e32 v134, v130
	v_mov_b32_e32 v135, v130
	v_mov_b32_e32 v136, v130
	v_mov_b32_e32 v137, v130
	v_mov_b32_e32 v142, v130
	v_mov_b32_e32 v143, v130
	v_mov_b32_e32 v144, v130
	v_mov_b32_e32 v145, v130
	v_mov_b32_e32 v150, v130
	v_mov_b32_e32 v151, v130
	v_mov_b32_e32 v152, v130
	v_mov_b32_e32 v153, v130
	v_mov_b32_e32 v138, v130
	v_mov_b32_e32 v139, v130
	v_mov_b32_e32 v140, v130
	v_mov_b32_e32 v141, v130
	v_mov_b32_e32 v146, v130
	v_mov_b32_e32 v147, v130
	v_mov_b32_e32 v148, v130
	v_mov_b32_e32 v149, v130
	s_waitcnt vmcnt(0) lgkmcnt(0)
	s_barrier
	s_mul_i32 s6, s34, s98
	s_mul_hi_u32 s7, s34, s98
	s_lshl_b64 s[6:7], s[6:7], 1
	s_add_u32 s6, s12, s6
	s_addc_u32 s7, s13, s7
	s_mul_i32 s8, s24, s98
	s_mul_hi_u32 s9, s24, s98
	s_lshl_b64 s[8:9], s[8:9], 1
	s_add_u32 s8, s16, s8
	s_addc_u32 s9, s17, s9
	v_and_b32_e32 v130, 63, v204
	v_lshrrev_b32_e32 v131, 6, v204
	v_lshrrev_b32_e32 v132, 3, v204
	v_lshrrev_b32_e32 v0, 4, v130
	v_lshl_add_u32 v0, v131, 2, v0
	v_xor_b32_e32 v0, v0, v130
	v_and_b32_e32 v0, 7, v0
	v_lshlrev_b32_e32 v133, 4, v0
	v_mul_lo_u32 v0, v132, s98
	v_lshl_add_u32 v232, v0, 1, v133
	s_lshl_b32 s28, s98, 7
	v_add_u32_e32 v233, s28, v232
	v_add_u32_e32 v234, s28, v233
	v_add_u32_e32 v235, s28, v234
	v_and_b32_e32 v0, 31, v132
	v_lshrrev_b32_e32 v130, 5, v132
	v_lshl_add_u32 v0, v130, 6, v0
	v_mul_lo_u32 v0, v0, s98
	v_lshl_add_u32 v236, v0, 1, v133
	s_lshl_b32 s28, s98, 6
	v_add_u32_e32 v237, s28, v236
	s_lshl_b32 s28, s98, 8
	v_add_u32_e32 v238, s28, v236
	v_add_u32_e32 v239, s28, v237
	s_lshr_b32 s25, s98, 6
	s_add_i32 s25, s25, -2
	v_and_b32_e32 v132, 31, v204
	v_lshrrev_b32_e32 v0, 2, v131
	v_lshl_add_u32 v0, v0, 6, v132
	v_lshlrev_b32_e32 v244, 7, v0
	v_and_b32_e32 v0, 3, v131
	v_lshl_add_u32 v0, v0, 5, v132
	v_lshlrev_b32_e32 v245, 7, v0
	v_bfe_u32 v0, v204, 5, 1
	v_bfe_u32 v130, v132, 1, 3
	v_or_b32_e32 v133, 0, v0
	v_xor_b32_e32 v133, v133, v130
	v_lshlrev_b32_e32 v240, 4, v133
	v_or_b32_e32 v133, 2, v0
	v_xor_b32_e32 v133, v133, v130
	v_lshlrev_b32_e32 v241, 4, v133
	v_or_b32_e32 v133, 4, v0
	v_xor_b32_e32 v133, v133, v130
	v_lshlrev_b32_e32 v242, 4, v133
	v_or_b32_e32 v133, 6, v0
	v_xor_b32_e32 v133, v133, v130
	v_lshlrev_b32_e32 v243, 4, v133
	v_lshlrev_b32_e32 v131, 10, v131
	s_nop 0
	v_readfirstlane_b32 s100, v131
	v_mov_b32_e32 v146, 0
	v_mov_b32_e32 v147, 0
	v_mov_b32_e32 v148, 0
	v_mov_b32_e32 v149, 0
	v_lshlrev_b32_e32 v130, 4, v204
	v_add_u32_e32 v132, 0x10000, v130
	s_mov_b64 exec, -1
	s_mov_b32 s11, 0
	s_mov_b32 s10, 0x10000
	s_waitcnt lgkmcnt(0)
	s_add_u32 m0, s100, 0x8000
	s_nop 0
	global_load_lds_dwordx4 v236, s[8:9]
	v_add_u32_e32 v236, 0x80, v236
	s_add_u32 m0, s100, 0xa000
	s_nop 0
	global_load_lds_dwordx4 v238, s[8:9]
	v_add_u32_e32 v238, 0x80, v238
	s_add_u32 m0, s100, 0x0
	s_nop 0
	global_load_lds_dwordx4 v232, s[6:7]
	v_add_u32_e32 v232, 0x80, v232
	s_add_u32 m0, s100, 0x2000
	s_nop 0
	global_load_lds_dwordx4 v234, s[6:7]
	v_add_u32_e32 v234, 0x80, v234
	s_add_u32 m0, s100, 0xc000
	s_nop 0
	global_load_lds_dwordx4 v237, s[8:9]
	v_add_u32_e32 v237, 0x80, v237
	s_add_u32 m0, s100, 0xe000
	s_nop 0
	global_load_lds_dwordx4 v239, s[8:9]
	v_add_u32_e32 v239, 0x80, v239
	s_add_u32 m0, s100, 0x4000
	s_nop 0
	global_load_lds_dwordx4 v233, s[6:7]
	v_add_u32_e32 v233, 0x80, v233
	s_add_u32 m0, s100, 0x6000
	s_nop 0
	global_load_lds_dwordx4 v235, s[6:7]
	v_add_u32_e32 v235, 0x80, v235
	s_cmp_eq_u32 s101, 1
	s_cbranch_scc0 .Lg8_m246_p0
	s_barrier

; DI int opaque_tid() { int t = threadIdx.x; asm volatile("" : "+v"(t)); return t; }
; template <bool SWAP>
; DI void gemm_mainloop(f32x16 (&acc)[4][2], const u16* __restrict__ A, int lda, int rlo, int rhi,
;                       const u16* __restrict__ B, int ldb, int K, char* lds, const u16* zero_line) {
;   const int tid = opaque_tid(), lane = tid & 63, w = tid >> 6;
;   const int wm = w >> 2, wn = w & 3;
;   const int h = lane >> 5, r = lane & 31;
;   const int lr = tid >> 3, lc = tid & 7;
; #pragma unroll
;   for (int mi = 0; mi < 4; ++mi)
; #pragma unroll
;     for (int ni = 0; ni < 2; ++ni)
; #pragma unroll
;       for (int i = 0; i < 16; ++i) acc[mi][ni][i] = 0.f;
;   const int gch = (lc ^ ((lr >> 1) & 7)) * 8;
;   const u16* ap = A + (ptrdiff_t)lr * lda + gch;
;   const u16* bp = B + (ptrdiff_t)lr * ldb + gch;
;   const int nk = K >> 6;
;   typedef __attribute__((address_space(3))) unsigned lds_u32;
;   auto glds = [&](int kt, int st) {
;     char* as_ = lds + st * 65536 + tid * 16;
; #pragma unroll
;     for (int i = 0; i < 4; ++i) {
;       const int rr = lr + 64 * i;
;       const u16* srca = (rr >= rlo && rr < rhi) ? (ap + (ptrdiff_t)(64 * i) * lda + kt * 64) : (zero_line + lc * 8);
;       __builtin_amdgcn_global_load_lds((const unsigned*)srca, (lds_u32*)(as_ + i * 8192), 16, 0, 0);
; template <int EPI>
; DI void phase_gemm(const Params& p, const GemmArgs& ga, char* lds) {
;     ...
;   for (int it = 0; it * (int)gridDim.x < total; ++it) {
;     const int lt = logical_index(it);
;     if (lt >= total) continue;
;     int mt, nt;
;     tile_mn(lt, Mt, ga.Nt, mt, nt);
;     int bb, tokbase, S, pos0, rlo = 0, rhi = 256;
;     if (EPI == EPI_UP) {
;       bb = 0; tokbase = 0; S = NTOK;
;       pos0 = 254 * mt - 1;
;       rlo = (mt == 0) ? 1 : 0;
;       rhi = NTOK - pos0; if (rhi > 256) rhi = 256;
;     } else {
;       seq_of_token(mt * 256, bb, tokbase, S);
;       pos0 = mt * 256 - tokbase;
;     }
;     const u16* A = ga.A + (ptrdiff_t)(tokbase + pos0) * ga.lda;
;     const u16* B = ga.Bt + (size_t)(nt * 256) * ga.K;
;     f32x16 acc[4][2];
;     bool swap;
;     if (EPI == EPI_M) swap = true;
;     else if (EPI == EPI_UP) swap = true;
;     else if (EPI == EPI_QKV1) swap = (nt < 8);
;     else swap = !(nt == 4 || nt == 5);
;     if (swap) gemm_mainloop<true>(acc, A, ga.lda, rlo, rhi, B, ga.K, ga.K, lds, (const u16*)(p.ws + OFF_ZERO));
.LBB0_315:
	s_add_i32 s6, s6, s25
	s_cmpk_gt_i32 s6, 0x6bf
	s_cbranch_scc1 .LBB0_314
	s_mul_hi_i32 s7, s6, 0x38e38e39
	s_lshr_b32 s8, s7, 31
	s_ashr_i32 s29, s7, 4
	s_add_i32 s29, s29, s8
	s_mul_i32 s7, s29, 0xffffffb8
	s_add_i32 s6, s7, s6
	s_ashr_i32 s8, s6, 31
	s_lshr_b32 s8, s8, 29
	s_lshl_b32 s7, s29, 3
	s_add_i32 s8, s6, s8
	s_add_i32 s6, s6, s7
	s_and_b32 s30, s8, -8
	s_sub_i32 s28, s6, s30
	s_lshl_b32 s12, s28, 8
	s_ashr_i32 s13, s12, 31
	s_ashr_i32 s9, s8, 3
	s_lshl_b64 s[6:7], s[12:13], 11
	s_add_u32 s14, s90, s6
	s_addc_u32 s15, s91, s7
	s_lshl_b32 s16, s9, 8
	s_ashr_i32 s17, s16, 31
	s_lshl_b64 s[6:7], s[16:17], 11
	s_add_u32 s20, s70, s6
	s_addc_u32 s21, s71, s7
	s_and_b32 s6, s9, -2
	s_cmp_lg_u32 s6, 4
	s_cselect_b64 s[18:19], -1, 0
	s_cmp_eq_u32 s6, 4
	s_mov_b64 s[6:7], -1
	s_cbranch_scc1 .LBB0_322
	s_waitcnt vmcnt(5)
	v_mov_b32_e32 v10, v204
	s_nop 0
	v_ashrrev_i32_e32 v2, 3, v10
	v_lshrrev_b32_e32 v13, 1, v2
	v_xor_b32_e32 v0, v13, v10
	v_ashrrev_i32_e32 v3, 31, v2
	v_lshlrev_b64 v[4:5], 11, v[2:3]
	v_lshlrev_b32_e32 v0, 4, v0
	v_and_b32_e32 v12, 31, v10
	v_lshl_add_u64 v[6:7], s[14:15], 0, v[4:5]
	v_and_b32_e32 v0, 0x70, v0
	v_lshl_add_u64 v[8:9], s[20:21], 0, v[4:5]
	s_waitcnt vmcnt(4)
	v_lshrrev_b32_e32 v14, 1, v10
	v_lshl_add_u64 v[6:7], v[6:7], 0, v[0:1]
	v_lshl_add_u64 v[164:165], v[8:9], 0, v[0:1]
	v_and_or_b32 v0, v14, s51, v12
	v_lshlrev_b32_e32 v161, 7, v0
	v_lshlrev_b32_e32 v0, 7, v10
	v_lshlrev_b32_e32 v174, 4, v10
	v_and_b32_e32 v163, 0x6f80, v0
	v_and_b32_e32 v0, 0x70, v174
	v_add_u32_e32 v175, 0x8000, v174
	v_lshl_add_u64 v[166:167], s[80:81], 0, v[0:1]
	v_cmp_gt_u32_e32 vcc, s50, v2
	v_readfirstlane_b32 s6, v174
	s_mov_b32 m0, s6
	v_cndmask_b32_e32 v9, v167, v7, vcc
	v_cndmask_b32_e32 v8, v166, v6, vcc
	v_readfirstlane_b32 s6, v175
	v_add_u32_e32 v0, 64, v2
	s_barrier
	s_mov_b32 m0, s6
	s_mov_b64 s[10:11], 0x20000
	v_cmp_gt_u32_e64 s[6:7], s50, v0
	v_add_u32_e32 v0, 0x2000, v174
	v_lshl_add_u64 v[8:9], v[6:7], 0, s[10:11]
	v_readfirstlane_b32 s8, v0
	v_add_u32_e32 v176, 0xa000, v174
	v_cndmask_b32_e64 v9, v167, v9, s[6:7]
	v_cndmask_b32_e64 v8, v166, v8, s[6:7]
	s_mov_b32 m0, s8
	v_readfirstlane_b32 s8, v176
	v_lshl_add_u64 v[8:9], v[164:165], 0, s[10:11]
	s_mov_b32 m0, s8
	v_add_u32_e32 v3, 0x80, v2
	s_mov_b64 s[22:23], 0x40000
	v_add_u32_e32 v177, 0x4000, v174
	v_lshl_add_u64 v[8:9], v[6:7], 0, s[22:23]
	v_cmp_gt_u32_e64 s[8:9], s50, v3
	v_readfirstlane_b32 s10, v177
	v_add_u32_e32 v178, 0xc000, v174
	v_cndmask_b32_e64 v9, v167, v9, s[8:9]
	v_cndmask_b32_e64 v8, v166, v8, s[8:9]
	s_mov_b32 m0, s10
	v_readfirstlane_b32 s10, v178
	v_lshl_add_u64 v[8:9], v[164:165], 0, s[22:23]
	s_mov_b32 m0, s10
	s_mov_b64 s[22:23], 0x60000
	v_add_u32_e32 v8, 0xc0, v2
	v_add_u32_e32 v179, 0x6000, v174
	v_lshl_add_u64 v[2:3], v[6:7], 0, s[22:23]
	v_cmp_gt_u32_e64 s[10:11], s50, v8
	v_readfirstlane_b32 s17, v179
	v_add_u32_e32 v180, 0xe000, v174
	v_cndmask_b32_e64 v3, v167, v3, s[10:11]
	v_cndmask_b32_e64 v2, v166, v2, s[10:11]
	s_mov_b32 m0, s17
	v_readfirstlane_b32 s17, v180
	v_lshl_add_u64 v[2:3], v[164:165], 0, s[22:23]
	s_mov_b32 m0, s17
	v_bfe_u32 v11, v10, 5, 1
	s_sub_i32 s17, s26, s30
	s_lshl_b32 s22, s29, 6
	v_bfe_u32 v15, v10, 1, 3
	v_bitop3_b32 v2, v14, v11, 7 bitop3:0x6c
	s_sub_i32 s17, s17, s22
	v_lshlrev_b32_e32 v181, 4, v2
	v_bitop3_b32 v2, v11, v15, 2 bitop3:0x36
	s_lshl_b32 s22, s17, 8
	v_lshlrev_b32_e32 v182, 4, v2
	v_bitop3_b32 v2, v11, v15, 4 bitop3:0x36
	s_ashr_i32 s23, s22, 31
	v_lshlrev_b32_e32 v183, 4, v2
	v_bitop3_b32 v2, v11, v15, 6 bitop3:0x36
	s_lshl_b64 s[22:23], s[22:23], 11
	v_lshlrev_b32_e32 v186, 4, v2
	v_lshl_add_u64 v[2:3], v[4:5], 0, s[22:23]
	v_bitop3_b32 v4, v13, 7, v10 bitop3:0x48
	s_waitcnt vmcnt(0)
	v_lshl_or_b32 v2, v4, 4, v2
	v_lshl_add_u64 v[168:169], s[70:71], 0, v[2:3]
	v_mov_b32_e32 v130, 0
	v_mov_b32_e32 v2, 0
	s_mov_b32 s13, 1
	v_add_u32_e32 v187, 0x10000, v174
	v_add_u32_e32 v192, 0x18000, v174
	v_add_u32_e32 v193, 0x12000, v174
	v_add_u32_e32 v194, 0x1a000, v174
	v_add_u32_e32 v195, 0x14000, v174
	v_add_u32_e32 v196, 0x1c000, v174
	v_add_u32_e32 v197, 0x16000, v174
	v_add_u32_e32 v198, 0x1e000, v174
	v_add_u32_e32 v199, 0x10000, v161
	v_or_b32_e32 v200, 0x10000, v163
	s_mov_b64 s[22:23], 0
	v_mov_b32_e32 v3, v2
	v_mov_b32_e32 v4, v2
	v_mov_b32_e32 v5, v2
	v_mov_b32_e32 v6, v2
	v_mov_b32_e32 v7, v2
	v_mov_b32_e32 v8, v2
	v_mov_b32_e32 v9, v2
	v_mov_b32_e32 v10, v2
	v_mov_b32_e32 v11, v2
	v_mov_b32_e32 v12, v2
	v_mov_b32_e32 v13, v2
	v_mov_b32_e32 v14, v2
	v_mov_b32_e32 v15, v2
	v_mov_b32_e32 v16, v2
	v_mov_b32_e32 v17, v2
	v_mov_b32_e32 v34, v2
	v_mov_b32_e32 v35, v2
	v_mov_b32_e32 v36, v2
	v_mov_b32_e32 v37, v2
	v_mov_b32_e32 v38, v2
	v_mov_b32_e32 v39, v2
	v_mov_b32_e32 v40, v2
	v_mov_b32_e32 v41, v2
	v_mov_b32_e32 v42, v2
	v_mov_b32_e32 v43, v2
	v_mov_b32_e32 v44, v2
	v_mov_b32_e32 v45, v2
	v_mov_b32_e32 v46, v2
	v_mov_b32_e32 v47, v2
	v_mov_b32_e32 v48, v2
	v_mov_b32_e32 v49, v2
	s_waitcnt vmcnt(0)
; template <bool SWAP>
; DI void gemm_mainloop(f32x16 (&acc)[4][2], const u16* __restrict__ A, int lda, int rlo, int rhi,
;                       const u16* __restrict__ B, int ldb, int K, char* lds, const u16* zero_line) {
;     ...
; #pragma unroll
;   for (int mi = 0; mi < 4; ++mi)
; #pragma unroll
;     for (int ni = 0; ni < 2; ++ni)
; #pragma unroll
;       for (int i = 0; i < 16; ++i) acc[mi][ni][i] = 0.f;
;   const int gch = (lc ^ ((lr >> 1) & 7)) * 8;
;   const u16* ap = A + (ptrdiff_t)lr * lda + gch;
;   const u16* bp = B + (ptrdiff_t)lr * ldb + gch;
;   const int nk = K >> 6;
;   typedef __attribute__((address_space(3))) unsigned lds_u32;
;   auto glds = [&](int kt, int st) {
;     char* as_ = lds + st * 65536 + tid * 16;
; #pragma unroll
;     for (int i = 0; i < 4; ++i) {
;       const int rr = lr + 64 * i;
;       const u16* srca = (rr >= rlo && rr < rhi) ? (ap + (ptrdiff_t)(64 * i) * lda + kt * 64) : (zero_line + lc * 8);
;       __builtin_amdgcn_global_load_lds((const unsigned*)srca, (lds_u32*)(as_ + i * 8192), 16, 0, 0);
;       __builtin_amdgcn_global_load_lds((const unsigned*)(bp + (ptrdiff_t)(64 * i) * ldb + kt * 64), (lds_u32*)(as_ + 32768 + i * 8192), 16, 0, 0);
;     }
;   };
;   const int sw = (r >> 1) & 7;
;   const int arow_off = (wm * 128 + r) * 128;
;   const int brow_off = 32768 + (wn * 64 + r) * 128;
;   __syncthreads();
;   glds(0, 0);
;   asm volatile("s_waitcnt vmcnt(0)" ::: "memory");
;   __syncthreads();
	v_mov_b32_e32 v18, v2
	v_mov_b32_e32 v19, v2
	v_mov_b32_e32 v20, v2
	v_mov_b32_e32 v21, v2
	v_mov_b32_e32 v22, v2
	v_mov_b32_e32 v23, v2
	v_mov_b32_e32 v24, v2
	v_mov_b32_e32 v25, v2
	v_mov_b32_e32 v26, v2
	v_mov_b32_e32 v27, v2
	v_mov_b32_e32 v28, v2
	v_mov_b32_e32 v29, v2
	v_mov_b32_e32 v30, v2
	v_mov_b32_e32 v31, v2
	v_mov_b32_e32 v32, v2
	v_mov_b32_e32 v33, v2
	v_mov_b32_e32 v66, v2
	v_mov_b32_e32 v67, v2
	v_mov_b32_e32 v68, v2
	v_mov_b32_e32 v69, v2
	v_mov_b32_e32 v70, v2
	v_mov_b32_e32 v71, v2
	v_mov_b32_e32 v72, v2
	v_mov_b32_e32 v73, v2
	v_mov_b32_e32 v74, v2
	v_mov_b32_e32 v75, v2
	v_mov_b32_e32 v76, v2
	v_mov_b32_e32 v77, v2
	v_mov_b32_e32 v78, v2
	v_mov_b32_e32 v79, v2
	v_mov_b32_e32 v80, v2
	v_mov_b32_e32 v81, v2
	v_mov_b32_e32 v50, v2
	v_mov_b32_e32 v51, v2
	v_mov_b32_e32 v52, v2
	v_mov_b32_e32 v53, v2
	v_mov_b32_e32 v54, v2
	v_mov_b32_e32 v55, v2
	v_mov_b32_e32 v56, v2
	v_mov_b32_e32 v57, v2
	v_mov_b32_e32 v58, v2
	v_mov_b32_e32 v59, v2
	v_mov_b32_e32 v60, v2
	v_mov_b32_e32 v61, v2
	v_mov_b32_e32 v62, v2
	v_mov_b32_e32 v63, v2
	v_mov_b32_e32 v64, v2
	v_mov_b32_e32 v65, v2
	v_mov_b32_e32 v98, v2
	v_mov_b32_e32 v99, v2
	v_mov_b32_e32 v100, v2
	v_mov_b32_e32 v101, v2
	v_mov_b32_e32 v102, v2
	v_mov_b32_e32 v103, v2
	v_mov_b32_e32 v104, v2
	v_mov_b32_e32 v105, v2
	v_mov_b32_e32 v106, v2
	v_mov_b32_e32 v107, v2
	v_mov_b32_e32 v108, v2
	v_mov_b32_e32 v109, v2
	v_mov_b32_e32 v110, v2
	v_mov_b32_e32 v111, v2
	v_mov_b32_e32 v112, v2
	v_mov_b32_e32 v113, v2
	v_mov_b32_e32 v82, v2
	v_mov_b32_e32 v83, v2
	v_mov_b32_e32 v84, v2
	v_mov_b32_e32 v85, v2
	v_mov_b32_e32 v86, v2
	v_mov_b32_e32 v87, v2
	v_mov_b32_e32 v88, v2
	v_mov_b32_e32 v89, v2
	v_mov_b32_e32 v90, v2
	v_mov_b32_e32 v91, v2
	v_mov_b32_e32 v92, v2
	v_mov_b32_e32 v93, v2
	v_mov_b32_e32 v94, v2
	v_mov_b32_e32 v95, v2
	v_mov_b32_e32 v96, v2
	v_mov_b32_e32 v97, v2
	v_mov_b32_e32 v114, v2
	v_mov_b32_e32 v115, v2
	v_mov_b32_e32 v116, v2
	v_mov_b32_e32 v117, v2
	v_mov_b32_e32 v118, v2
	v_mov_b32_e32 v119, v2
	v_mov_b32_e32 v120, v2
	v_mov_b32_e32 v121, v2
	v_mov_b32_e32 v122, v2
	v_mov_b32_e32 v123, v2
	v_mov_b32_e32 v124, v2
	v_mov_b32_e32 v125, v2
	v_mov_b32_e32 v126, v2
	v_mov_b32_e32 v127, v2
	v_mov_b32_e32 v128, v2
	v_mov_b32_e32 v129, v2
	v_mov_b32_e32 v131, v130
	v_mov_b32_e32 v132, v130
	v_mov_b32_e32 v133, v130
	v_mov_b32_e32 v134, v130
	v_mov_b32_e32 v135, v130
	v_mov_b32_e32 v136, v130
	v_mov_b32_e32 v137, v130
	v_mov_b32_e32 v138, v130
	v_mov_b32_e32 v139, v130
	v_mov_b32_e32 v140, v130
	v_mov_b32_e32 v141, v130
	v_mov_b32_e32 v146, v130
	v_mov_b32_e32 v147, v130
	v_mov_b32_e32 v148, v130
	v_mov_b32_e32 v149, v130
	v_mov_b32_e32 v142, v130
	v_mov_b32_e32 v143, v130
	v_mov_b32_e32 v144, v130
	v_mov_b32_e32 v145, v130
	v_mov_b32_e32 v150, v130
	v_mov_b32_e32 v151, v130
	v_mov_b32_e32 v152, v130
	v_mov_b32_e32 v153, v130
	s_waitcnt lgkmcnt(0)
	s_barrier
	s_ashr_i32 s7, s12, 31
	s_mov_b32 s6, s12
	s_lshl_b64 s[6:7], s[6:7], 11
	s_add_u32 s6, s90, s6
	s_addc_u32 s7, s91, s7
	s_ashr_i32 s9, s16, 31
	s_mov_b32 s8, s16
	s_lshl_b64 s[8:9], s[8:9], 11
	s_add_u32 s8, s70, s8
	s_addc_u32 s9, s71, s9
	v_and_b32_e32 v130, 63, v204
	v_lshrrev_b32_e32 v131, 6, v204
	v_lshrrev_b32_e32 v132, 3, v204
	v_lshrrev_b32_e32 v0, 4, v130
	v_lshl_add_u32 v0, v131, 2, v0
	v_xor_b32_e32 v0, v0, v130
	v_and_b32_e32 v0, 7, v0
	v_lshlrev_b32_e32 v133, 4, v0
	v_lshl_add_u32 v240, v132, 11, v133
	v_add_u32_e32 v241, 0x20000, v240
	v_add_u32_e32 v242, 0x40000, v240
	v_add_u32_e32 v243, 0x60000, v240
	v_and_b32_e32 v0, 31, v132
	v_lshrrev_b32_e32 v130, 5, v132
	v_lshl_add_u32 v0, v130, 6, v0
	v_lshl_add_u32 v244, v0, 11, v133
	v_add_u32_e32 v245, 0x10000, v244
	v_add_u32_e32 v246, 0x40000, v244
	v_add_u32_e32 v247, 0x50000, v244
	v_and_b32_e32 v132, 31, v204
	v_lshrrev_b32_e32 v0, 2, v131
	v_lshl_add_u32 v0, v0, 6, v132
	v_lshlrev_b32_e32 v166, 7, v0
	v_and_b32_e32 v0, 3, v131
	v_lshl_add_u32 v0, v0, 5, v132
	v_lshlrev_b32_e32 v249, 7, v0
	v_bfe_u32 v0, v204, 5, 1
	v_bfe_u32 v130, v132, 1, 3
	v_or_b32_e32 v133, 0, v0
	v_xor_b32_e32 v133, v133, v130
	v_lshlrev_b32_e32 v161, 4, v133
	v_or_b32_e32 v133, 2, v0
	v_xor_b32_e32 v133, v133, v130
	v_lshlrev_b32_e32 v163, 4, v133
	v_or_b32_e32 v133, 4, v0
	v_xor_b32_e32 v133, v133, v130
	v_lshlrev_b32_e32 v164, 4, v133
	v_or_b32_e32 v133, 6, v0
	v_xor_b32_e32 v133, v133, v130
	v_lshlrev_b32_e32 v165, 4, v133
	v_lshlrev_b32_e32 v131, 10, v131
	s_nop 0
	v_readfirstlane_b32 s100, v131
	v_mov_b32_e32 v146, 0
	v_mov_b32_e32 v147, 0
	v_mov_b32_e32 v148, 0
	v_mov_b32_e32 v149, 0
	v_lshlrev_b32_e32 v130, 4, v204
	v_add_u32_e32 v132, 0x10000, v130
	s_mov_b64 exec, -1
	s_mov_b32 s11, 0
	s_mov_b32 s10, 0x10000
	s_waitcnt lgkmcnt(0)
	s_add_u32 m0, s100, 0x8000
	s_nop 0
	global_load_lds_dwordx4 v244, s[8:9]
	v_add_u32_e32 v244, 0x80, v244
	s_add_u32 m0, s100, 0xa000
	s_nop 0
	global_load_lds_dwordx4 v246, s[8:9]
	v_add_u32_e32 v246, 0x80, v246
	s_add_u32 m0, s100, 0x0
	s_nop 0
	global_load_lds_dwordx4 v240, s[6:7]
	v_add_u32_e32 v240, 0x80, v240
	s_add_u32 m0, s100, 0x2000
	s_nop 0
	global_load_lds_dwordx4 v242, s[6:7]
	v_add_u32_e32 v242, 0x80, v242
	s_add_u32 m0, s100, 0xc000
	s_nop 0
	global_load_lds_dwordx4 v245, s[8:9]
	v_add_u32_e32 v245, 0x80, v245
	s_add_u32 m0, s100, 0xe000
	s_nop 0
	global_load_lds_dwordx4 v247, s[8:9]
	v_add_u32_e32 v247, 0x80, v247
	s_add_u32 m0, s100, 0x4000
	s_nop 0
	global_load_lds_dwordx4 v241, s[6:7]
	v_add_u32_e32 v241, 0x80, v241
	s_add_u32 m0, s100, 0x6000
	s_nop 0
	global_load_lds_dwordx4 v243, s[6:7]
	v_add_u32_e32 v243, 0x80, v243
	s_cmp_eq_u32 s101, 1
	s_cbranch_scc0 .Lg8_ia_p0
	s_barrier

; DI int opaque_tid() { int t = threadIdx.x; asm volatile("" : "+v"(t)); return t; }
; template <bool SWAP>
; DI void gemm_mainloop(f32x16 (&acc)[4][2], const u16* __restrict__ A, int lda, int rlo, int rhi,
;                       const u16* __restrict__ B, int ldb, int K, char* lds, const u16* zero_line) {
;   const int tid = opaque_tid(), lane = tid & 63, w = tid >> 6;
;   const int wm = w >> 2, wn = w & 3;
;   const int h = lane >> 5, r = lane & 31;
;   const int lr = tid >> 3, lc = tid & 7;
; #pragma unroll
;   for (int mi = 0; mi < 4; ++mi)
; #pragma unroll
;     for (int ni = 0; ni < 2; ++ni)
; #pragma unroll
;       for (int i = 0; i < 16; ++i) acc[mi][ni][i] = 0.f;
;   const int gch = (lc ^ ((lr >> 1) & 7)) * 8;
;   const u16* ap = A + (ptrdiff_t)lr * lda + gch;
;   const u16* bp = B + (ptrdiff_t)lr * ldb + gch;
;   const int nk = K >> 6;
;   typedef __attribute__((address_space(3))) unsigned lds_u32;
;   auto glds = [&](int kt, int st) {
;     char* as_ = lds + st * 65536 + tid * 16;
; #pragma unroll
;     for (int i = 0; i < 4; ++i) {
;       const int rr = lr + 64 * i;
;       const u16* srca = (rr >= rlo && rr < rhi) ? (ap + (ptrdiff_t)(64 * i) * lda + kt * 64) : (zero_line + lc * 8);
;       __builtin_amdgcn_global_load_lds((const unsigned*)srca, (lds_u32*)(as_ + i * 8192), 16, 0, 0);
; template <int EPI>
; DI void phase_gemm(const Params& p, const GemmArgs& ga, char* lds) {
;     ...
;   for (int it = 0; it * (int)gridDim.x < total; ++it) {
;     const int lt = logical_index(it);
;     if (lt >= total) continue;
;     int mt, nt;
;     tile_mn(lt, Mt, ga.Nt, mt, nt);
;     int bb, tokbase, S, pos0, rlo = 0, rhi = 256;
;     if (EPI == EPI_UP) {
;       bb = 0; tokbase = 0; S = NTOK;
;       pos0 = 254 * mt - 1;
;       rlo = (mt == 0) ? 1 : 0;
;       rhi = NTOK - pos0; if (rhi > 256) rhi = 256;
;     } else {
;       seq_of_token(mt * 256, bb, tokbase, S);
;       pos0 = mt * 256 - tokbase;
;     }
;     const u16* A = ga.A + (ptrdiff_t)(tokbase + pos0) * ga.lda;
;     const u16* B = ga.Bt + (size_t)(nt * 256) * ga.K;
;     f32x16 acc[4][2];
;     bool swap;
;     if (EPI == EPI_M) swap = true;
;     else if (EPI == EPI_UP) swap = true;
;     else if (EPI == EPI_QKV1) swap = (nt < 8);
;     else swap = !(nt == 4 || nt == 5);
;     if (swap) gemm_mainloop<true>(acc, A, ga.lda, rlo, rhi, B, ga.K, ga.K, lds, (const u16*)(p.ws + OFF_ZERO));
.LBB0_322:
	s_and_b64 vcc, exec, s[6:7]
	s_cbranch_vccz .LBB0_328
	s_waitcnt vmcnt(5)
	s_nop 8
	v_mov_b32_e32 v10, v204
	s_nop 0
	v_ashrrev_i32_e32 v2, 3, v10
	v_lshrrev_b32_e32 v13, 1, v2
	v_xor_b32_e32 v0, v13, v10
	v_ashrrev_i32_e32 v3, 31, v2
	v_lshlrev_b64 v[4:5], 11, v[2:3]
	v_lshlrev_b32_e32 v0, 4, v0
	v_and_b32_e32 v12, 31, v10
	v_lshl_add_u64 v[6:7], s[14:15], 0, v[4:5]
	v_and_b32_e32 v0, 0x70, v0
	v_lshl_add_u64 v[8:9], s[20:21], 0, v[4:5]
	s_waitcnt vmcnt(4)
	v_lshrrev_b32_e32 v14, 1, v10
	v_lshl_add_u64 v[6:7], v[6:7], 0, v[0:1]
	v_lshl_add_u64 v[164:165], v[8:9], 0, v[0:1]
	v_and_or_b32 v0, v14, s51, v12
	v_lshlrev_b32_e32 v161, 7, v0
	v_lshlrev_b32_e32 v0, 7, v10
	v_lshlrev_b32_e32 v174, 4, v10
	v_and_b32_e32 v163, 0x6f80, v0
	v_and_b32_e32 v0, 0x70, v174
	v_add_u32_e32 v175, 0x8000, v174
	v_lshl_add_u64 v[166:167], s[80:81], 0, v[0:1]
	v_cmp_gt_u32_e32 vcc, s50, v2
	v_readfirstlane_b32 s6, v174
	s_mov_b32 m0, s6
	v_cndmask_b32_e32 v9, v167, v7, vcc
	v_cndmask_b32_e32 v8, v166, v6, vcc
	v_readfirstlane_b32 s6, v175
	v_add_u32_e32 v0, 64, v2
	s_barrier
	s_mov_b32 m0, s6
	s_mov_b64 s[10:11], 0x20000
	v_cmp_gt_u32_e64 s[6:7], s50, v0
	v_add_u32_e32 v0, 0x2000, v174
	v_lshl_add_u64 v[8:9], v[6:7], 0, s[10:11]
	v_readfirstlane_b32 s8, v0
	v_add_u32_e32 v176, 0xa000, v174
	v_cndmask_b32_e64 v9, v167, v9, s[6:7]
	v_cndmask_b32_e64 v8, v166, v8, s[6:7]
	s_mov_b32 m0, s8
	v_readfirstlane_b32 s8, v176
	v_lshl_add_u64 v[8:9], v[164:165], 0, s[10:11]
	s_mov_b32 m0, s8
	v_add_u32_e32 v3, 0x80, v2
	s_mov_b64 s[14:15], 0x40000
	v_add_u32_e32 v177, 0x4000, v174
	v_lshl_add_u64 v[8:9], v[6:7], 0, s[14:15]
	v_cmp_gt_u32_e64 s[8:9], s50, v3
	v_readfirstlane_b32 s10, v177
	v_add_u32_e32 v178, 0xc000, v174
	v_cndmask_b32_e64 v9, v167, v9, s[8:9]
	v_cndmask_b32_e64 v8, v166, v8, s[8:9]
	s_mov_b32 m0, s10
	v_readfirstlane_b32 s10, v178
	v_lshl_add_u64 v[8:9], v[164:165], 0, s[14:15]
	s_mov_b32 m0, s10
	s_mov_b64 s[20:21], 0x60000
	v_add_u32_e32 v8, 0xc0, v2
	v_add_u32_e32 v179, 0x6000, v174
	v_lshl_add_u64 v[2:3], v[6:7], 0, s[20:21]
	v_cmp_gt_u32_e64 s[10:11], s50, v8
	v_readfirstlane_b32 s14, v179
	v_add_u32_e32 v180, 0xe000, v174
	v_cndmask_b32_e64 v3, v167, v3, s[10:11]
	v_cndmask_b32_e64 v2, v166, v2, s[10:11]
	s_mov_b32 m0, s14
	v_readfirstlane_b32 s14, v180
	v_lshl_add_u64 v[2:3], v[164:165], 0, s[20:21]
	s_mov_b32 m0, s14
	v_bfe_u32 v11, v10, 5, 1
	s_sub_i32 s14, s26, s30
	s_lshl_b32 s15, s29, 6
	v_bfe_u32 v15, v10, 1, 3
	v_bitop3_b32 v2, v14, v11, 7 bitop3:0x6c
	s_sub_i32 s14, s14, s15
	v_lshlrev_b32_e32 v181, 4, v2
	v_bitop3_b32 v2, v11, v15, 2 bitop3:0x36
	s_lshl_b32 s14, s14, 8
	v_lshlrev_b32_e32 v182, 4, v2
	v_bitop3_b32 v2, v11, v15, 4 bitop3:0x36
	s_ashr_i32 s15, s14, 31
	v_lshlrev_b32_e32 v183, 4, v2
	v_bitop3_b32 v2, v11, v15, 6 bitop3:0x36
	s_lshl_b64 s[14:15], s[14:15], 11
	v_lshlrev_b32_e32 v186, 4, v2
	v_lshl_add_u64 v[2:3], v[4:5], 0, s[14:15]
	v_bitop3_b32 v4, v13, 7, v10 bitop3:0x48
	s_waitcnt vmcnt(0)
	v_lshl_or_b32 v2, v4, 4, v2
	v_lshl_add_u64 v[168:169], s[70:71], 0, v[2:3]
	v_mov_b32_e32 v130, 0
	v_mov_b32_e32 v2, 0
	s_mov_b32 s13, 1
	v_add_u32_e32 v187, 0x10000, v174
	v_add_u32_e32 v192, 0x18000, v174
	v_add_u32_e32 v193, 0x12000, v174
	v_add_u32_e32 v194, 0x1a000, v174
	v_add_u32_e32 v195, 0x14000, v174
	v_add_u32_e32 v196, 0x1c000, v174
	v_add_u32_e32 v197, 0x16000, v174
	v_add_u32_e32 v198, 0x1e000, v174
	v_add_u32_e32 v199, 0x10000, v161
	v_or_b32_e32 v200, 0x10000, v163
	s_mov_b64 s[14:15], 0
	v_mov_b32_e32 v3, v2
	v_mov_b32_e32 v4, v2
	v_mov_b32_e32 v5, v2
	v_mov_b32_e32 v6, v2
	v_mov_b32_e32 v7, v2
	v_mov_b32_e32 v8, v2
	v_mov_b32_e32 v9, v2
	v_mov_b32_e32 v10, v2
	v_mov_b32_e32 v11, v2
	v_mov_b32_e32 v12, v2
	v_mov_b32_e32 v13, v2
	v_mov_b32_e32 v14, v2
	v_mov_b32_e32 v15, v2
	v_mov_b32_e32 v16, v2
	v_mov_b32_e32 v17, v2
	v_mov_b32_e32 v34, v2
	v_mov_b32_e32 v35, v2
	v_mov_b32_e32 v36, v2
	v_mov_b32_e32 v37, v2
	v_mov_b32_e32 v38, v2
	v_mov_b32_e32 v39, v2
	v_mov_b32_e32 v40, v2
	v_mov_b32_e32 v41, v2
	v_mov_b32_e32 v42, v2
	v_mov_b32_e32 v43, v2
	v_mov_b32_e32 v44, v2
	v_mov_b32_e32 v45, v2
	v_mov_b32_e32 v46, v2
	v_mov_b32_e32 v47, v2
	v_mov_b32_e32 v48, v2
	v_mov_b32_e32 v49, v2
	s_waitcnt vmcnt(0)
; template <bool SWAP>
; DI void gemm_mainloop(f32x16 (&acc)[4][2], const u16* __restrict__ A, int lda, int rlo, int rhi,
;                       const u16* __restrict__ B, int ldb, int K, char* lds, const u16* zero_line) {
;     ...
; #pragma unroll
;   for (int mi = 0; mi < 4; ++mi)
; #pragma unroll
;     for (int ni = 0; ni < 2; ++ni)
; #pragma unroll
;       for (int i = 0; i < 16; ++i) acc[mi][ni][i] = 0.f;
;   const int gch = (lc ^ ((lr >> 1) & 7)) * 8;
;   const u16* ap = A + (ptrdiff_t)lr * lda + gch;
;   const u16* bp = B + (ptrdiff_t)lr * ldb + gch;
;   const int nk = K >> 6;
;   typedef __attribute__((address_space(3))) unsigned lds_u32;
;   auto glds = [&](int kt, int st) {
;     char* as_ = lds + st * 65536 + tid * 16;
; #pragma unroll
;     for (int i = 0; i < 4; ++i) {
;       const int rr = lr + 64 * i;
;       const u16* srca = (rr >= rlo && rr < rhi) ? (ap + (ptrdiff_t)(64 * i) * lda + kt * 64) : (zero_line + lc * 8);
;       __builtin_amdgcn_global_load_lds((const unsigned*)srca, (lds_u32*)(as_ + i * 8192), 16, 0, 0);
;       __builtin_amdgcn_global_load_lds((const unsigned*)(bp + (ptrdiff_t)(64 * i) * ldb + kt * 64), (lds_u32*)(as_ + 32768 + i * 8192), 16, 0, 0);
;     }
;   };
;   const int sw = (r >> 1) & 7;
;   const int arow_off = (wm * 128 + r) * 128;
;   const int brow_off = 32768 + (wn * 64 + r) * 128;
;   __syncthreads();
;   glds(0, 0);
;   asm volatile("s_waitcnt vmcnt(0)" ::: "memory");
;   __syncthreads();
	v_mov_b32_e32 v18, v2
	v_mov_b32_e32 v19, v2
	v_mov_b32_e32 v20, v2
	v_mov_b32_e32 v21, v2
	v_mov_b32_e32 v22, v2
	v_mov_b32_e32 v23, v2
	v_mov_b32_e32 v24, v2
	v_mov_b32_e32 v25, v2
	v_mov_b32_e32 v26, v2
	v_mov_b32_e32 v27, v2
	v_mov_b32_e32 v28, v2
	v_mov_b32_e32 v29, v2
	v_mov_b32_e32 v30, v2
	v_mov_b32_e32 v31, v2
	v_mov_b32_e32 v32, v2
	v_mov_b32_e32 v33, v2
	v_mov_b32_e32 v66, v2
	v_mov_b32_e32 v67, v2
	v_mov_b32_e32 v68, v2
	v_mov_b32_e32 v69, v2
	v_mov_b32_e32 v70, v2
	v_mov_b32_e32 v71, v2
	v_mov_b32_e32 v72, v2
	v_mov_b32_e32 v73, v2
	v_mov_b32_e32 v74, v2
	v_mov_b32_e32 v75, v2
	v_mov_b32_e32 v76, v2
	v_mov_b32_e32 v77, v2
	v_mov_b32_e32 v78, v2
	v_mov_b32_e32 v79, v2
	v_mov_b32_e32 v80, v2
	v_mov_b32_e32 v81, v2
	v_mov_b32_e32 v50, v2
	v_mov_b32_e32 v51, v2
	v_mov_b32_e32 v52, v2
	v_mov_b32_e32 v53, v2
	v_mov_b32_e32 v54, v2
	v_mov_b32_e32 v55, v2
	v_mov_b32_e32 v56, v2
	v_mov_b32_e32 v57, v2
	v_mov_b32_e32 v58, v2
	v_mov_b32_e32 v59, v2
	v_mov_b32_e32 v60, v2
	v_mov_b32_e32 v61, v2
	v_mov_b32_e32 v62, v2
	v_mov_b32_e32 v63, v2
	v_mov_b32_e32 v64, v2
	v_mov_b32_e32 v65, v2
	v_mov_b32_e32 v98, v2
	v_mov_b32_e32 v99, v2
	v_mov_b32_e32 v100, v2
	v_mov_b32_e32 v101, v2
	v_mov_b32_e32 v102, v2
	v_mov_b32_e32 v103, v2
	v_mov_b32_e32 v104, v2
	v_mov_b32_e32 v105, v2
	v_mov_b32_e32 v106, v2
	v_mov_b32_e32 v107, v2
	v_mov_b32_e32 v108, v2
	v_mov_b32_e32 v109, v2
	v_mov_b32_e32 v110, v2
	v_mov_b32_e32 v111, v2
	v_mov_b32_e32 v112, v2
	v_mov_b32_e32 v113, v2
	v_mov_b32_e32 v82, v2
	v_mov_b32_e32 v83, v2
	v_mov_b32_e32 v84, v2
	v_mov_b32_e32 v85, v2
	v_mov_b32_e32 v86, v2
	v_mov_b32_e32 v87, v2
	v_mov_b32_e32 v88, v2
	v_mov_b32_e32 v89, v2
	v_mov_b32_e32 v90, v2
	v_mov_b32_e32 v91, v2
	v_mov_b32_e32 v92, v2
	v_mov_b32_e32 v93, v2
	v_mov_b32_e32 v94, v2
	v_mov_b32_e32 v95, v2
	v_mov_b32_e32 v96, v2
	v_mov_b32_e32 v97, v2
	v_mov_b32_e32 v114, v2
	v_mov_b32_e32 v115, v2
	v_mov_b32_e32 v116, v2
	v_mov_b32_e32 v117, v2
	v_mov_b32_e32 v118, v2
	v_mov_b32_e32 v119, v2
	v_mov_b32_e32 v120, v2
	v_mov_b32_e32 v121, v2
	v_mov_b32_e32 v122, v2
	v_mov_b32_e32 v123, v2
	v_mov_b32_e32 v124, v2
	v_mov_b32_e32 v125, v2
	v_mov_b32_e32 v126, v2
	v_mov_b32_e32 v127, v2
	v_mov_b32_e32 v128, v2
	v_mov_b32_e32 v129, v2
	v_mov_b32_e32 v131, v130
	v_mov_b32_e32 v132, v130
	v_mov_b32_e32 v133, v130
	v_mov_b32_e32 v134, v130
	v_mov_b32_e32 v135, v130
	v_mov_b32_e32 v136, v130
	v_mov_b32_e32 v137, v130
	v_mov_b32_e32 v138, v130
	v_mov_b32_e32 v139, v130
	v_mov_b32_e32 v140, v130
	v_mov_b32_e32 v141, v130
	v_mov_b32_e32 v146, v130
	v_mov_b32_e32 v147, v130
	v_mov_b32_e32 v148, v130
	v_mov_b32_e32 v149, v130
	v_mov_b32_e32 v142, v130
	v_mov_b32_e32 v143, v130
	v_mov_b32_e32 v144, v130
	v_mov_b32_e32 v145, v130
	v_mov_b32_e32 v150, v130
	v_mov_b32_e32 v151, v130
	v_mov_b32_e32 v152, v130
	v_mov_b32_e32 v153, v130
	s_waitcnt lgkmcnt(0)
	s_barrier
	s_ashr_i32 s7, s12, 31
	s_mov_b32 s6, s12
	s_lshl_b64 s[6:7], s[6:7], 11
	s_add_u32 s6, s90, s6
	s_addc_u32 s7, s91, s7
	s_ashr_i32 s9, s16, 31
	s_mov_b32 s8, s16
	s_lshl_b64 s[8:9], s[8:9], 11
	s_add_u32 s8, s70, s8
	s_addc_u32 s9, s71, s9
	v_and_b32_e32 v130, 63, v204
	v_lshrrev_b32_e32 v131, 6, v204
	v_lshrrev_b32_e32 v132, 3, v204
	v_lshrrev_b32_e32 v0, 4, v130
	v_lshl_add_u32 v0, v131, 2, v0
	v_xor_b32_e32 v0, v0, v130
	v_and_b32_e32 v0, 7, v0
	v_lshlrev_b32_e32 v133, 4, v0
	v_lshl_add_u32 v240, v132, 11, v133
	v_add_u32_e32 v241, 0x20000, v240
	v_add_u32_e32 v242, 0x40000, v240
	v_add_u32_e32 v243, 0x60000, v240
	v_and_b32_e32 v0, 31, v132
	v_lshrrev_b32_e32 v130, 5, v132
	v_lshl_add_u32 v0, v130, 6, v0
	v_lshl_add_u32 v244, v0, 11, v133
	v_add_u32_e32 v245, 0x10000, v244
	v_add_u32_e32 v246, 0x40000, v244
	v_add_u32_e32 v247, 0x50000, v244
	v_and_b32_e32 v132, 31, v204
	v_lshrrev_b32_e32 v0, 2, v131
	v_lshl_add_u32 v0, v0, 6, v132
	v_lshlrev_b32_e32 v166, 7, v0
	v_and_b32_e32 v0, 3, v131
	v_lshl_add_u32 v0, v0, 5, v132
	v_lshlrev_b32_e32 v249, 7, v0
	v_bfe_u32 v0, v204, 5, 1
	v_bfe_u32 v130, v132, 1, 3
	v_or_b32_e32 v133, 0, v0
	v_xor_b32_e32 v133, v133, v130
	v_lshlrev_b32_e32 v161, 4, v133
	v_or_b32_e32 v133, 2, v0
	v_xor_b32_e32 v133, v133, v130
	v_lshlrev_b32_e32 v163, 4, v133
	v_or_b32_e32 v133, 4, v0
	v_xor_b32_e32 v133, v133, v130
	v_lshlrev_b32_e32 v164, 4, v133
	v_or_b32_e32 v133, 6, v0
	v_xor_b32_e32 v133, v133, v130
	v_lshlrev_b32_e32 v165, 4, v133
	v_lshlrev_b32_e32 v131, 10, v131
	s_nop 0
	v_readfirstlane_b32 s100, v131
	v_mov_b32_e32 v146, 0
	v_mov_b32_e32 v147, 0
	v_mov_b32_e32 v148, 0
	v_mov_b32_e32 v149, 0
	v_lshlrev_b32_e32 v130, 4, v204
	v_add_u32_e32 v132, 0x10000, v130
	s_mov_b64 exec, -1
	s_mov_b32 s11, 0
	s_mov_b32 s10, 0x10000
	s_waitcnt lgkmcnt(0)
	s_add_u32 m0, s100, 0x8000
	s_nop 0
	global_load_lds_dwordx4 v244, s[8:9]
	v_add_u32_e32 v244, 0x80, v244
	s_add_u32 m0, s100, 0xa000
	s_nop 0
	global_load_lds_dwordx4 v246, s[8:9]
	v_add_u32_e32 v246, 0x80, v246
	s_add_u32 m0, s100, 0x0
	s_nop 0
	global_load_lds_dwordx4 v240, s[6:7]
	v_add_u32_e32 v240, 0x80, v240
	s_add_u32 m0, s100, 0x2000
	s_nop 0
	global_load_lds_dwordx4 v242, s[6:7]
	v_add_u32_e32 v242, 0x80, v242
	s_add_u32 m0, s100, 0xc000
	s_nop 0
	global_load_lds_dwordx4 v245, s[8:9]
	v_add_u32_e32 v245, 0x80, v245
	s_add_u32 m0, s100, 0xe000
	s_nop 0
	global_load_lds_dwordx4 v247, s[8:9]
	v_add_u32_e32 v247, 0x80, v247
	s_add_u32 m0, s100, 0x4000
	s_nop 0
	global_load_lds_dwordx4 v241, s[6:7]
	v_add_u32_e32 v241, 0x80, v241
	s_add_u32 m0, s100, 0x6000
	s_nop 0
	global_load_lds_dwordx4 v243, s[6:7]
	v_add_u32_e32 v243, 0x80, v243
	s_cmp_eq_u32 s101, 1
	s_cbranch_scc0 .Lg8_ib_p0
	s_barrier

; DI void phase_ln(const Params& p, int layer, int sub, bool first, bool final_, const u16* M, int glayer, int goff) {
;     ...
;   const int nw = gridDim.x * 8, gw = blockIdx.x * 8 + w;
;   const int rows_per = (NTOK + nw - 1) / nw;
;   const int r0 = gw * rows_per;
;   const int r1 = (r0 + rows_per < NTOK) ? (r0 + rows_per) : NTOK;
;   if (r0 >= r1) return;
;   auto load_row = [&](int row, float4 (&v)[4], u32x2 (&mm)[4]) {
;     const float* xr = first ? xin_row(p, row) : (p.out + (size_t)row * DM);
; #pragma unroll
;     for (int j = 0; j < 4; ++j) {
;       const f32x4v t_ = __builtin_nontemporal_load((const f32x4v*)(xr + j * 256 + lane * 4));
;       v[j] = (float4){t_.x, t_.y, t_.z, t_.w};
;     }
;     if (M) {
; #pragma unroll
;       for (int j = 0; j < 4; ++j) mm[j] = *(const u32x2*)(M + (size_t)row * DM + j * 256 + lane * 4);
;     }
;   };
;   float4 pg[4], psh[4], pgm[4];
;   int cur_bb = -1;
;   float4 v[4], vn[4], vn2[4];
;   u32x2 mm[4], mmn[4], mmn2[4];
; #pragma unroll
;   for (int j = 0; j < 4; ++j) {
;     mm[j] = (u32x2){0u, 0u}; mmn[j] = (u32x2){0u, 0u}; mmn2[j] = (u32x2){0u, 0u};
;     vn[j] = (float4){0.f, 0.f, 0.f, 0.f}; vn2[j] = (float4){0.f, 0.f, 0.f, 0.f};
;   }
;   load_row(r0, v, mm);
;   if (r0 + 1 < r1) load_row(r0 + 1, vn, mmn);
.LBB0_389:
	s_andn2_b64 vcc, exec, s[6:7]
	s_cbranch_vccnz .LBB0_9
	s_cmp_gt_i32 s84, 0
	s_mov_b64 s[6:7], -1
	s_cbranch_scc0 .LBB0_401
	s_waitcnt vmcnt(6)
	v_mov_b32_e32 v6, v204
	s_load_dword s6, s[74:75], 0x0
	v_ashrrev_i32_e32 v2, 6, v6
	v_readlane_b32 s8, v253, 14
	s_waitcnt lgkmcnt(0)
	s_lshl_b32 s6, s6, 3
	s_abs_i32 s7, s6
	v_cvt_f32_u32_e32 v0, s7
	s_sub_i32 s9, 0, s7
	v_add_u32_e32 v2, s8, v2
	s_add_i32 s8, s6, 0xbfff
	v_rcp_iflag_f32_e32 v0, v0
	s_xor_b32 s6, s8, s6
	s_abs_i32 s8, s8
	s_ashr_i32 s6, s6, 31
	v_mul_f32_e32 v0, 0x4f7ffffe, v0
	v_cvt_u32_f32_e32 v0, v0
	s_nop 0
	v_readfirstlane_b32 s10, v0
	s_mul_i32 s9, s9, s10
	s_mul_hi_u32 s9, s10, s9
	s_add_i32 s10, s10, s9
	s_mul_hi_u32 s9, s8, s10
	s_mul_i32 s10, s9, s7
	s_sub_i32 s8, s8, s10
	s_add_i32 s11, s9, 1
	s_sub_i32 s10, s8, s7
	s_cmp_ge_u32 s8, s7
	s_cselect_b32 s9, s11, s9
	s_cselect_b32 s8, s10, s8
	s_add_i32 s10, s9, 1
	s_cmp_ge_u32 s8, s7
	s_cselect_b32 s7, s10, s9
	s_xor_b32 s7, s7, s6
	s_sub_i32 s6, s7, s6
	s_waitcnt vmcnt(5)
	v_mul_lo_u32 v66, s6, v2
	v_add_u32_e32 v0, s6, v66
	v_min_i32_e32 v94, 0xc000, v0
	v_cmp_lt_i32_e32 vcc, v66, v94
	s_and_saveexec_b64 s[6:7], vcc
	s_cbranch_execz .LBB0_400
	v_add_u32_e32 v0, 0xffff8000, v66
	v_cmp_gt_i32_e32 vcc, s48, v66
	v_mov_b32_e32 v4, s17
	v_ashrrev_i32_e32 v67, 31, v66
	v_cndmask_b32_e32 v2, v0, v66, vcc
	v_mov_b32_e32 v0, s19
	v_cndmask_b32_e32 v5, v0, v4, vcc
	v_mov_b32_e32 v0, s18
	v_mov_b32_e32 v4, s16
	v_cndmask_b32_e32 v3, 0, v67, vcc
	v_cndmask_b32_e32 v4, v0, v4, vcc
	v_lshlrev_b32_e32 v0, 2, v6
	v_lshlrev_b64 v[2:3], 12, v[2:3]
	v_and_b32_e32 v7, 0xfc, v0
	v_lshl_add_u64 v[2:3], v[4:5], 0, v[2:3]
	v_lshlrev_b32_e32 v0, 2, v7
	v_lshl_add_u64 v[2:3], v[2:3], 0, v[0:1]
	global_load_dwordx4 v[26:29], v[2:3], off
	global_load_dwordx4 v[34:37], v[2:3], off offset:1024
	global_load_dwordx4 v[22:25], v[2:3], off offset:2048
	global_load_dwordx4 v[30:33], v[2:3], off offset:3072
	v_add_u32_e32 v9, 1, v66
	v_cmp_lt_i32_e32 vcc, v9, v94
	v_mov_b32_e32 v8, 0
	v_mov_b32_e32 v4, 0
	v_mov_b32_e32 v5, 0
	v_mov_b32_e32 v2, 0
	v_mov_b32_e32 v3, 0
	v_mov_b32_e32 v12, 0
	v_mov_b32_e32 v13, 0
	v_mov_b32_e32 v10, 0
	v_mov_b32_e32 v11, 0
	s_waitcnt vmcnt(8)
	v_mov_b32_e32 v16, 0
	v_mov_b32_e32 v17, 0
	v_mov_b32_e32 v14, 0
	v_mov_b32_e32 v15, 0
	s_waitcnt vmcnt(7)
	v_mov_b32_e32 v20, 0
	v_mov_b32_e32 v21, 0
	v_mov_b32_e32 v18, 0
	v_mov_b32_e32 v19, 0
	s_and_saveexec_b64 s[8:9], vcc
	s_cbranch_execz .LBB0_394
	s_movk_i32 s10, 0x7fff
	v_add_u32_e32 v2, 0xffff8001, v66
	v_ashrrev_i32_e32 v3, 31, v9
	v_cmp_gt_i32_e32 vcc, s10, v66
	v_mov_b32_e32 v4, s19
	v_mov_b32_e32 v5, s17
	v_cndmask_b32_e32 v3, 0, v3, vcc
	v_cndmask_b32_e32 v2, v2, v9, vcc
	v_cndmask_b32_e32 v5, v4, v5, vcc
	v_mov_b32_e32 v4, s18
	v_mov_b32_e32 v9, s16
	v_cndmask_b32_e32 v4, v4, v9, vcc
	v_lshlrev_b64 v[2:3], 12, v[2:3]
	v_lshl_add_u64 v[2:3], v[4:5], 0, v[2:3]
	v_lshl_add_u64 v[18:19], v[2:3], 0, v[0:1]
	global_load_dwordx4 v[2:5], v[18:19], off
	global_load_dwordx4 v[10:13], v[18:19], off offset:1024
	global_load_dwordx4 v[14:17], v[18:19], off offset:2048
	s_nop 0
	global_load_dwordx4 v[18:21], v[18:19], off offset:3072

; DI void phase_ln(const Params& p, int layer, int sub, bool first, bool final_, const u16* M, int glayer, int goff) {
;     ...
;   auto load_row = [&](int row, float4 (&v)[4], u32x2 (&mm)[4]) {
;     const float* xr = first ? xin_row(p, row) : (p.out + (size_t)row * DM);
; #pragma unroll
;     for (int j = 0; j < 4; ++j) {
;       const f32x4v t_ = __builtin_nontemporal_load((const f32x4v*)(xr + j * 256 + lane * 4));
;       v[j] = (float4){t_.x, t_.y, t_.z, t_.w};
;     }
;     if (M) {
; #pragma unroll
;       for (int j = 0; j < 4; ++j) mm[j] = *(const u32x2*)(M + (size_t)row * DM + j * 256 + lane * 4);
;     }
;   };
;     ...
;     if (row + 2 < r1) load_row(row + 2, vn2, mmn2);
.LBB0_396:
	v_add_u32_e32 v67, 2, v66
	v_cmp_lt_i32_e32 vcc, v67, v94
	s_and_saveexec_b64 s[10:11], vcc
	s_cbranch_execz .LBB0_398
	s_movk_i32 s12, 0x7ffe
	v_add_u32_e32 v6, 0xffff8002, v66
	v_ashrrev_i32_e32 v7, 31, v67
	v_cmp_gt_i32_e32 vcc, s12, v66
	v_mov_b32_e32 v8, s19
	v_mov_b32_e32 v9, s17
	v_cndmask_b32_e32 v7, 0, v7, vcc
	v_cndmask_b32_e32 v6, v6, v67, vcc
	v_cndmask_b32_e32 v9, v8, v9, vcc
	v_mov_b32_e32 v8, s18
	v_mov_b32_e32 v46, s16
	v_cndmask_b32_e32 v8, v8, v46, vcc
	v_lshlrev_b64 v[6:7], 12, v[6:7]
	v_lshl_add_u64 v[6:7], v[8:9], 0, v[6:7]
	v_lshl_add_u64 v[58:59], v[6:7], 0, v[0:1]
	global_load_dwordx4 v[6:9], v[58:59], off
	global_load_dwordx4 v[46:49], v[58:59], off offset:1024
	global_load_dwordx4 v[54:57], v[58:59], off offset:2048
	s_nop 0
	global_load_dwordx4 v[58:61], v[58:59], off offset:3072
